# attention epilogue: O rows staged through the wave's own LDS ring pieces, 8 dwordx4 stores per wave instead of 64 short stores
# baseline (speedup 1.0000x reference)
.LBB0_418:
.LBB0_419:
	s_lshr_b32 s0, s3, 7
	s_lshl_b32 s0, s0, 23
	s_and_b32 s1, s3, 15
	s_lshl_b32 s1, s1, 19
	s_or_b32 s0, s0, s1
	s_bfe_u32 s1, s3, 0x30004
	s_lshl_b32 s1, s1, 8
	s_or_b32 s0, s0, s1
	s_add_u32 s60, s25, s0
	s_addc_u32 s61, s28, 0
	s_add_u32 s46, s21, s0
	s_addc_u32 s47, s24, 0
	s_lshr_b32 s1, s3, 6
	s_mul_i32 s1, s1, 0x110000
	s_add_u32 s62, s9, s1
	s_addc_u32 s63, s20, 0
	s_add_u32 s64, s29, s1
	s_addc_u32 s65, s30, 0
	v_readfirstlane_b32 s44, v1
	s_lshr_b32 s6, s44, 6
	s_lshl_b32 s45, s6, 10
	s_lshl_b32 s44, s6, 9
	s_add_i32 s44, s44, 0x20000
	v_and_b32_e32 v136, 15, v1
	v_bfe_u32 v137, v1, 4, 2
	v_lshrrev_b32_e32 v130, 4, v1
	v_xor_b32_e32 v131, v1, v130
	v_and_b32_e32 v131, 15, v131
	v_lshlrev_b32_e32 v131, 4, v131
	v_lshl_or_b32 v150, v130, 8, v131
	v_add_u32_e32 v151, 0x2000, v150
	v_and_b32_e32 v131, 7, v130
	v_lshlrev_b32_e32 v131, 1, v131
	v_xor_b32_e32 v131, v1, v131
	v_and_b32_e32 v131, 15, v131
	v_lshlrev_b32_e32 v131, 4, v131
	v_lshl_or_b32 v152, v130, 8, v131
	v_add_u32_e32 v153, 0x2000, v152
	v_lshlrev_b32_e32 v130, 8, v136
	v_add_u32_e32 v131, 0, v137
	v_xor_b32_e32 v131, v131, v136
	v_lshl_or_b32 v183, v131, 4, v130
	v_add_u32_e32 v187, 0x10000, v183
	v_add_u32_e32 v131, 4, v137
	v_xor_b32_e32 v131, v131, v136
	v_lshl_or_b32 v184, v131, 4, v130
	v_add_u32_e32 v188, 0x10000, v184
	v_add_u32_e32 v131, 8, v137
	v_xor_b32_e32 v131, v131, v136
	v_lshl_or_b32 v185, v131, 4, v130
	v_add_u32_e32 v189, 0x10000, v185
	v_add_u32_e32 v131, 12, v137
	v_xor_b32_e32 v131, v131, v136
	v_lshl_or_b32 v186, v131, 4, v130
	v_add_u32_e32 v190, 0x10000, v186
	v_bfe_u32 v130, v1, 2, 2
	v_lshl_or_b32 v131, v137, 2, v130
	v_and_b32_e32 v132, 7, v131
	v_and_b32_e32 v133, 3, v1
	v_lshlrev_b32_e32 v133, 3, v133
	v_lshl_or_b32 v133, v131, 8, v133
	v_xor_b32_e32 v134, 0, v132
	v_lshl_or_b32 v240, v134, 5, v133
	v_add_u32_e32 v142, 0x10000, v240
	v_xor_b32_e32 v134, 1, v132
	v_lshl_or_b32 v241, v134, 5, v133
	v_add_u32_e32 v143, 0x10000, v241
	v_xor_b32_e32 v134, 2, v132
	v_lshl_or_b32 v242, v134, 5, v133
	v_add_u32_e32 v144, 0x10000, v242
	v_xor_b32_e32 v134, 3, v132
	v_lshl_or_b32 v243, v134, 5, v133
	v_add_u32_e32 v145, 0x10000, v243
	v_xor_b32_e32 v134, 4, v132
	v_lshl_or_b32 v244, v134, 5, v133
	v_add_u32_e32 v146, 0x10000, v244
	v_xor_b32_e32 v134, 5, v132
	v_lshl_or_b32 v245, v134, 5, v133
	v_add_u32_e32 v147, 0x10000, v245
	v_xor_b32_e32 v134, 6, v132
	v_lshl_or_b32 v246, v134, 5, v133
	v_add_u32_e32 v148, 0x10000, v246
	v_xor_b32_e32 v134, 7, v132
	v_lshl_or_b32 v247, v134, 5, v133
	v_add_u32_e32 v149, 0x10000, v247
	s_lshl_b32 s18, s6, 16
	v_lshlrev_b32_e32 v130, 11, v136
	v_lshl_or_b32 v130, v137, 4, v130
	v_add_u32_e32 v154, s18, v130
	v_add_u32_e32 v155, 0x8000, v154
	v_lshlrev_b32_e32 v130, 13, v137
	v_lshl_or_b32 v130, v136, 1, v130
	v_add_u32_e32 v156, s18, v130
	v_add_u32_e32 v157, 0x1000, v156
	v_add_u32_e32 v158, 0x8000, v156
	v_add_u32_e32 v159, 0x9000, v156
	s_lshl_b32 s19, s6, 10
	s_add_i32 s19, s19, 0x10000
	v_lshlrev_b32_e32 v130, 13, v137
	v_lshl_or_b32 v130, v136, 1, v130
	v_add_u32_e32 v156, s19, v130
	v_and_b32_e32 v130, 63, v1
	v_lshlrev_b32_e32 v131, 4, v130
	v_add_u32_e32 v157, s19, v131
	v_lshrrev_b32_e32 v131, 4, v130
	v_lshlrev_b32_e32 v131, 11, v131
	v_and_b32_e32 v130, 15, v130
	v_lshl_or_b32 v131, v130, 4, v131
	v_add_u32_e32 v158, s18, v131
	v_and_b32_e32 v130, 63, v1
	v_lshl_add_u32 v160, v130, 2, s44
	v_lshl_add_u32 v161, v137, 4, s44
	s_add_i32 m0, s45, 0x0
	s_nop 0
	global_load_lds_dwordx4 v152, s[64:65]
	s_add_i32 m0, s45, 0x4000
	s_nop 0
	global_load_lds_dwordx4 v150, s[62:63]
	s_add_i32 m0, s45, 0x2000
	s_nop 0
	global_load_lds_dwordx4 v153, s[64:65]
	s_add_i32 m0, s45, 0x6000
	s_nop 0
	global_load_lds_dwordx4 v151, s[62:63]
	s_add_u32 s62, s62, 0x4000
	s_addc_u32 s63, s63, 0
	s_add_u32 s64, s64, 0x4000
	s_addc_u32 s65, s65, 0
	s_add_i32 m0, s45, 0x8000
	s_nop 0
	global_load_lds_dwordx4 v152, s[64:65]
	s_add_i32 m0, s45, 0xc000
	s_nop 0
	global_load_lds_dwordx4 v150, s[62:63]
	s_add_i32 m0, s45, 0xa000
	s_nop 0
	global_load_lds_dwordx4 v153, s[64:65]
	s_add_i32 m0, s45, 0xe000
	s_nop 0
	global_load_lds_dwordx4 v151, s[62:63]
	s_add_u32 s62, s62, 0x4000
	s_addc_u32 s63, s63, 0
	s_add_u32 s64, s64, 0x4000
	s_addc_u32 s65, s65, 0
	global_load_dwordx4 v[98:101], v154, s[60:61]
	global_load_dwordx4 v[102:105], v154, s[60:61] offset:64
	global_load_dwordx4 v[106:109], v154, s[60:61] offset:128
	global_load_dwordx4 v[110:113], v154, s[60:61] offset:192
	global_load_dwordx4 v[114:117], v155, s[60:61]
	global_load_dwordx4 v[118:121], v155, s[60:61] offset:64
	global_load_dwordx4 v[122:125], v155, s[60:61] offset:128
	global_load_dwordx4 v[126:129], v155, s[60:61] offset:192
	v_mov_b32_e32 v2, 0
	v_mov_b32_e32 v3, 0
	v_mov_b32_e32 v4, 0
	v_mov_b32_e32 v5, 0
	v_mov_b32_e32 v6, 0
	v_mov_b32_e32 v7, 0
	v_mov_b32_e32 v8, 0
	v_mov_b32_e32 v9, 0
	v_mov_b32_e32 v10, 0
	v_mov_b32_e32 v11, 0
	v_mov_b32_e32 v12, 0
	v_mov_b32_e32 v13, 0
	v_mov_b32_e32 v14, 0
	v_mov_b32_e32 v15, 0
	v_mov_b32_e32 v16, 0
	v_mov_b32_e32 v17, 0
	v_mov_b32_e32 v18, 0
	v_mov_b32_e32 v19, 0
	v_mov_b32_e32 v20, 0
	v_mov_b32_e32 v21, 0
	v_mov_b32_e32 v22, 0
	v_mov_b32_e32 v23, 0
	v_mov_b32_e32 v24, 0
	v_mov_b32_e32 v25, 0
	v_mov_b32_e32 v26, 0
	v_mov_b32_e32 v27, 0
	v_mov_b32_e32 v28, 0
	v_mov_b32_e32 v29, 0
	v_mov_b32_e32 v30, 0
	v_mov_b32_e32 v31, 0
	v_mov_b32_e32 v32, 0
	v_mov_b32_e32 v33, 0
	v_mov_b32_e32 v34, 0
	v_mov_b32_e32 v35, 0
	v_mov_b32_e32 v36, 0
	v_mov_b32_e32 v37, 0
	v_mov_b32_e32 v38, 0
	v_mov_b32_e32 v39, 0
	v_mov_b32_e32 v40, 0
	v_mov_b32_e32 v41, 0
	v_mov_b32_e32 v42, 0
	v_mov_b32_e32 v43, 0
	v_mov_b32_e32 v44, 0
	v_mov_b32_e32 v45, 0
	v_mov_b32_e32 v46, 0
	v_mov_b32_e32 v47, 0
	v_mov_b32_e32 v48, 0
	v_mov_b32_e32 v49, 0
	v_mov_b32_e32 v50, 0
	v_mov_b32_e32 v51, 0
	v_mov_b32_e32 v52, 0
	v_mov_b32_e32 v53, 0
	v_mov_b32_e32 v54, 0
	v_mov_b32_e32 v55, 0
	v_mov_b32_e32 v56, 0
	v_mov_b32_e32 v57, 0
	v_mov_b32_e32 v58, 0
	v_mov_b32_e32 v59, 0
	v_mov_b32_e32 v60, 0
	v_mov_b32_e32 v61, 0
	v_mov_b32_e32 v62, 0
	v_mov_b32_e32 v63, 0
	v_mov_b32_e32 v64, 0
	v_mov_b32_e32 v65, 0
	v_mov_b32_e32 v165, 0
	v_mov_b32_e32 v163, 0
	s_waitcnt vmcnt(0)

.Lattn_loop:
	s_waitcnt lgkmcnt(6)
	v_mfma_f32_16x16x32_bf16 v[192:195], v[166:169], v[98:101], 0
	v_mfma_f32_16x16x32_bf16 v[208:211], v[166:169], v[114:117], 0
	ds_read_b128 v[166:169], v185 offset:49152
	s_add_i32 m0, s45, 0x18000
	v_add_f32_e32 v130, v66, v67
	v_add_f32_e32 v131, v68, v69
	v_add_f32_e32 v130, v70, v130
	global_load_lds_dwordx4 v152, s[64:65]
	v_mfma_f32_16x16x32_bf16 v[196:199], v[170:173], v[98:101], 0
	v_mfma_f32_16x16x32_bf16 v[212:215], v[170:173], v[114:117], 0
	ds_read_b128 v[170:173], v185 offset:53248
	s_add_i32 m0, s45, 0x1c000
	v_add_f32_e32 v131, v71, v131
	v_add_f32_e32 v130, v72, v130
	v_add_f32_e32 v131, v73, v131
	global_load_lds_dwordx4 v150, s[62:63]
	s_waitcnt lgkmcnt(6)
	v_mfma_f32_16x16x32_bf16 v[200:203], v[174:177], v[98:101], 0
	v_mfma_f32_16x16x32_bf16 v[216:219], v[174:177], v[114:117], 0
	ds_read_b128 v[174:177], v185 offset:57344
	s_add_i32 m0, s45, 0x1a000
	v_add_f32_e32 v130, v74, v130
	v_add_f32_e32 v131, v75, v131
	v_add_f32_e32 v130, v76, v130
	global_load_lds_dwordx4 v153, s[64:65]
	v_mfma_f32_16x16x32_bf16 v[204:207], v[178:181], v[98:101], 0
	v_mfma_f32_16x16x32_bf16 v[220:223], v[178:181], v[114:117], 0
	ds_read_b128 v[178:181], v185 offset:61440
	s_add_i32 m0, s45, 0x1e000
	v_add_f32_e32 v131, v77, v131
	v_add_f32_e32 v130, v78, v130
	v_add_f32_e32 v131, v79, v131
	global_load_lds_dwordx4 v151, s[62:63]
	s_add_u32 s62, s62, 0x4000
	s_addc_u32 s63, s63, 0
	s_add_u32 s64, s64, 0x4000
	s_addc_u32 s65, s65, 0
	s_waitcnt lgkmcnt(6)
	v_mfma_f32_16x16x32_bf16 v[192:195], v[224:227], v[102:105], v[192:195]
	v_mfma_f32_16x16x32_bf16 v[208:211], v[224:227], v[118:121], v[208:211]
	ds_read_b128 v[224:227], v186 offset:49152
	v_add_f32_e32 v130, v80, v130
	v_add_f32_e32 v131, v81, v131
	v_add_f32_e32 v130, v130, v131
	v_mfma_f32_16x16x32_bf16 v[196:199], v[228:231], v[102:105], v[196:199]
	v_mfma_f32_16x16x32_bf16 v[212:215], v[228:231], v[118:121], v[212:215]
	ds_read_b128 v[228:231], v186 offset:53248
	v_add_f32_e32 v165, v165, v130
	v_add_f32_e32 v132, v82, v83
	v_add_f32_e32 v133, v84, v85
	s_waitcnt lgkmcnt(6)
	v_mfma_f32_16x16x32_bf16 v[200:203], v[232:235], v[102:105], v[200:203]
	v_mfma_f32_16x16x32_bf16 v[216:219], v[232:235], v[118:121], v[216:219]
	ds_read_b128 v[232:235], v186 offset:57344
	v_add_f32_e32 v132, v86, v132
	v_add_f32_e32 v133, v87, v133
	v_add_f32_e32 v132, v88, v132
	v_mfma_f32_16x16x32_bf16 v[204:207], v[236:239], v[102:105], v[204:207]
	v_mfma_f32_16x16x32_bf16 v[220:223], v[236:239], v[118:121], v[220:223]
	ds_read_b128 v[236:239], v186 offset:61440
	v_add_f32_e32 v133, v89, v133
	v_add_f32_e32 v132, v90, v132
	v_add_f32_e32 v133, v91, v133
	s_waitcnt lgkmcnt(6)
	v_mfma_f32_16x16x32_bf16 v[192:195], v[166:169], v[106:109], v[192:195]
	v_mfma_f32_16x16x32_bf16 v[208:211], v[166:169], v[122:125], v[208:211]
	ds_read_b64_tr_b16 v[166:167], v240 offset:0
	ds_read_b64_tr_b16 v[168:169], v240 offset:4096
	v_add_f32_e32 v132, v92, v132
	v_add_f32_e32 v133, v93, v133
	v_add_f32_e32 v132, v94, v132
	v_mfma_f32_16x16x32_bf16 v[196:199], v[170:173], v[106:109], v[196:199]
	v_mfma_f32_16x16x32_bf16 v[212:215], v[170:173], v[122:125], v[212:215]
	ds_read_b64_tr_b16 v[170:171], v241 offset:0
	ds_read_b64_tr_b16 v[172:173], v241 offset:4096
	v_add_f32_e32 v133, v95, v133
	v_add_f32_e32 v132, v96, v132
	v_add_f32_e32 v133, v97, v133
	s_waitcnt lgkmcnt(8)
	v_mfma_f32_16x16x32_bf16 v[200:203], v[174:177], v[106:109], v[200:203]
	v_mfma_f32_16x16x32_bf16 v[216:219], v[174:177], v[122:125], v[216:219]
	ds_read_b64_tr_b16 v[174:175], v242 offset:0
	ds_read_b64_tr_b16 v[176:177], v242 offset:4096
	v_add_f32_e32 v132, v132, v133
	v_add_f32_e32 v163, v163, v132
	v_cvt_pk_bf16_f32 v66, v66, v67
	v_mfma_f32_16x16x32_bf16 v[204:207], v[178:181], v[106:109], v[204:207]
	v_mfma_f32_16x16x32_bf16 v[220:223], v[178:181], v[122:125], v[220:223]
	ds_read_b64_tr_b16 v[178:179], v243 offset:0
	ds_read_b64_tr_b16 v[180:181], v243 offset:4096
	v_cvt_pk_bf16_f32 v67, v68, v69
	v_cvt_pk_bf16_f32 v68, v70, v71
	v_cvt_pk_bf16_f32 v69, v72, v73
	s_waitcnt lgkmcnt(10)
	v_mfma_f32_16x16x32_bf16 v[192:195], v[224:227], v[110:113], v[192:195]
	v_mfma_f32_16x16x32_bf16 v[208:211], v[224:227], v[126:129], v[208:211]
	ds_read_b64_tr_b16 v[224:225], v244 offset:0
	ds_read_b64_tr_b16 v[226:227], v244 offset:4096
	v_cvt_pk_bf16_f32 v74, v74, v75
	v_cvt_pk_bf16_f32 v75, v76, v77
	v_cvt_pk_bf16_f32 v76, v78, v79
	v_mfma_f32_16x16x32_bf16 v[196:199], v[228:231], v[110:113], v[196:199]
	v_mfma_f32_16x16x32_bf16 v[212:215], v[228:231], v[126:129], v[212:215]
	v_cvt_pk_bf16_f32 v77, v80, v81
	v_cvt_pk_bf16_f32 v82, v82, v83
	v_cvt_pk_bf16_f32 v83, v84, v85
	s_waitcnt lgkmcnt(10)
	v_mfma_f32_16x16x32_bf16 v[200:203], v[232:235], v[110:113], v[200:203]
	v_mfma_f32_16x16x32_bf16 v[216:219], v[232:235], v[126:129], v[216:219]
	v_cvt_pk_bf16_f32 v84, v86, v87
	v_cvt_pk_bf16_f32 v85, v88, v89
	v_cvt_pk_bf16_f32 v90, v90, v91
	v_mfma_f32_16x16x32_bf16 v[204:207], v[236:239], v[110:113], v[204:207]
	v_mfma_f32_16x16x32_bf16 v[220:223], v[236:239], v[126:129], v[220:223]
	v_cvt_pk_bf16_f32 v91, v92, v93
	v_cvt_pk_bf16_f32 v92, v94, v95
	v_cvt_pk_bf16_f32 v93, v96, v97
	s_waitcnt lgkmcnt(6)
	v_mfma_f32_16x16x32_bf16 v[2:5], v[66:69], v[166:169], v[2:5]
	v_mfma_f32_16x16x32_bf16 v[34:37], v[82:85], v[166:169], v[34:37]
	ds_read_b64_tr_b16 v[228:229], v245 offset:0
	ds_read_b64_tr_b16 v[230:231], v245 offset:4096
	v_mfma_f32_16x16x32_bf16 v[6:9], v[66:69], v[170:173], v[6:9]
	v_mfma_f32_16x16x32_bf16 v[38:41], v[82:85], v[170:173], v[38:41]
	ds_read_b64_tr_b16 v[232:233], v246 offset:0
	ds_read_b64_tr_b16 v[234:235], v246 offset:4096
	s_waitcnt lgkmcnt(6)
	v_mfma_f32_16x16x32_bf16 v[10:13], v[66:69], v[174:177], v[10:13]
	v_mfma_f32_16x16x32_bf16 v[42:45], v[82:85], v[174:177], v[42:45]
	ds_read_b64_tr_b16 v[236:237], v247 offset:0
	ds_read_b64_tr_b16 v[238:239], v247 offset:4096
	v_exp_f32_e32 v192, v192
	v_exp_f32_e32 v193, v193
	v_exp_f32_e32 v194, v194
	v_mfma_f32_16x16x32_bf16 v[14:17], v[66:69], v[178:181], v[14:17]
	v_mfma_f32_16x16x32_bf16 v[46:49], v[82:85], v[178:181], v[46:49]
	ds_read_b64_tr_b16 v[166:167], v240 offset:8192
	ds_read_b64_tr_b16 v[168:169], v240 offset:12288
	v_exp_f32_e32 v195, v195
	v_exp_f32_e32 v208, v208
	s_waitcnt lgkmcnt(6)
	v_mfma_f32_16x16x32_bf16 v[18:21], v[66:69], v[224:227], v[18:21]
	v_mfma_f32_16x16x32_bf16 v[50:53], v[82:85], v[224:227], v[50:53]
	ds_read_b64_tr_b16 v[170:171], v241 offset:8192
	ds_read_b64_tr_b16 v[172:173], v241 offset:12288
	v_exp_f32_e32 v209, v209
	v_exp_f32_e32 v210, v210
	v_mfma_f32_16x16x32_bf16 v[22:25], v[66:69], v[228:231], v[22:25]
	v_mfma_f32_16x16x32_bf16 v[54:57], v[82:85], v[228:231], v[54:57]
	ds_read_b64_tr_b16 v[174:175], v242 offset:8192
	ds_read_b64_tr_b16 v[176:177], v242 offset:12288
	v_exp_f32_e32 v211, v211
	v_exp_f32_e32 v196, v196
	v_exp_f32_e32 v197, v197
	s_waitcnt lgkmcnt(6)
	v_mfma_f32_16x16x32_bf16 v[26:29], v[66:69], v[232:235], v[26:29]
	v_mfma_f32_16x16x32_bf16 v[58:61], v[82:85], v[232:235], v[58:61]
	ds_read_b64_tr_b16 v[178:179], v243 offset:8192
	ds_read_b64_tr_b16 v[180:181], v243 offset:12288
	v_exp_f32_e32 v198, v198
	v_exp_f32_e32 v199, v199
	v_mfma_f32_16x16x32_bf16 v[30:33], v[66:69], v[236:239], v[30:33]
	v_mfma_f32_16x16x32_bf16 v[62:65], v[82:85], v[236:239], v[62:65]
	ds_read_b64_tr_b16 v[224:225], v244 offset:8192
	ds_read_b64_tr_b16 v[226:227], v244 offset:12288
	v_exp_f32_e32 v212, v212
	v_exp_f32_e32 v213, v213
	s_waitcnt lgkmcnt(6)
	v_mfma_f32_16x16x32_bf16 v[2:5], v[74:77], v[166:169], v[2:5]
	v_mfma_f32_16x16x32_bf16 v[34:37], v[90:93], v[166:169], v[34:37]
	ds_read_b64_tr_b16 v[228:229], v245 offset:8192
	ds_read_b64_tr_b16 v[230:231], v245 offset:12288
	ds_read_b128 v[166:169], v187 offset:16384
	v_exp_f32_e32 v214, v214
	v_exp_f32_e32 v215, v215
	v_mfma_f32_16x16x32_bf16 v[6:9], v[74:77], v[170:173], v[6:9]
	v_mfma_f32_16x16x32_bf16 v[38:41], v[90:93], v[170:173], v[38:41]
	ds_read_b64_tr_b16 v[232:233], v246 offset:8192
	ds_read_b64_tr_b16 v[234:235], v246 offset:12288
	ds_read_b128 v[170:173], v187 offset:20480
	v_exp_f32_e32 v200, v200
	v_exp_f32_e32 v201, v201
	v_exp_f32_e32 v202, v202
	s_waitcnt lgkmcnt(8)
	v_mfma_f32_16x16x32_bf16 v[10:13], v[74:77], v[174:177], v[10:13]
	v_mfma_f32_16x16x32_bf16 v[42:45], v[90:93], v[174:177], v[42:45]
	ds_read_b64_tr_b16 v[236:237], v247 offset:8192
	ds_read_b64_tr_b16 v[238:239], v247 offset:12288
	ds_read_b128 v[174:177], v187 offset:24576
	v_exp_f32_e32 v203, v203
	v_exp_f32_e32 v216, v216
	v_mfma_f32_16x16x32_bf16 v[14:17], v[74:77], v[178:181], v[14:17]
	v_mfma_f32_16x16x32_bf16 v[46:49], v[90:93], v[178:181], v[46:49]
	ds_read_b128 v[178:181], v187 offset:28672
	v_exp_f32_e32 v217, v217
	v_exp_f32_e32 v218, v218
	s_waitcnt lgkmcnt(8)
	v_mfma_f32_16x16x32_bf16 v[18:21], v[74:77], v[224:227], v[18:21]
	v_mfma_f32_16x16x32_bf16 v[50:53], v[90:93], v[224:227], v[50:53]
	ds_read_b128 v[224:227], v188 offset:16384
	v_exp_f32_e32 v219, v219
	v_exp_f32_e32 v204, v204
	v_exp_f32_e32 v205, v205
	v_mfma_f32_16x16x32_bf16 v[22:25], v[74:77], v[228:231], v[22:25]
	v_mfma_f32_16x16x32_bf16 v[54:57], v[90:93], v[228:231], v[54:57]
	ds_read_b128 v[228:231], v188 offset:20480
	v_exp_f32_e32 v206, v206
	v_exp_f32_e32 v207, v207
	s_waitcnt lgkmcnt(4)
	v_mfma_f32_16x16x32_bf16 v[26:29], v[74:77], v[232:235], v[26:29]
	v_mfma_f32_16x16x32_bf16 v[58:61], v[90:93], v[232:235], v[58:61]
	ds_read_b128 v[232:235], v188 offset:24576
	v_exp_f32_e32 v220, v220
	v_exp_f32_e32 v221, v221
	v_mfma_f32_16x16x32_bf16 v[30:33], v[74:77], v[236:239], v[30:33]
	v_mfma_f32_16x16x32_bf16 v[62:65], v[90:93], v[236:239], v[62:65]
	ds_read_b128 v[236:239], v188 offset:28672
	v_exp_f32_e32 v222, v222
	v_exp_f32_e32 v223, v223
	s_waitcnt vmcnt(0)
	s_barrier
	v_mfma_f32_16x16x32_bf16 v[66:69], v[166:169], v[98:101], 0
	v_mfma_f32_16x16x32_bf16 v[82:85], v[166:169], v[114:117], 0
	ds_read_b128 v[166:169], v189 offset:16384
	s_add_i32 m0, s45, 0x0
	v_add_f32_e32 v130, v192, v193
	v_add_f32_e32 v131, v194, v195
	v_add_f32_e32 v130, v196, v130
	global_load_lds_dwordx4 v152, s[64:65]
	v_mfma_f32_16x16x32_bf16 v[70:73], v[170:173], v[98:101], 0
	v_mfma_f32_16x16x32_bf16 v[86:89], v[170:173], v[114:117], 0
	ds_read_b128 v[170:173], v189 offset:20480
	s_add_i32 m0, s45, 0x4000
	v_add_f32_e32 v131, v197, v131
	v_add_f32_e32 v130, v198, v130
	v_add_f32_e32 v131, v199, v131
	global_load_lds_dwordx4 v150, s[62:63]
	s_waitcnt lgkmcnt(6)
	v_mfma_f32_16x16x32_bf16 v[74:77], v[174:177], v[98:101], 0
	v_mfma_f32_16x16x32_bf16 v[90:93], v[174:177], v[114:117], 0
	ds_read_b128 v[174:177], v189 offset:24576
	s_add_i32 m0, s45, 0x2000
	v_add_f32_e32 v130, v200, v130
	v_add_f32_e32 v131, v201, v131
	v_add_f32_e32 v130, v202, v130
	global_load_lds_dwordx4 v153, s[64:65]
	v_mfma_f32_16x16x32_bf16 v[78:81], v[178:181], v[98:101], 0
	v_mfma_f32_16x16x32_bf16 v[94:97], v[178:181], v[114:117], 0
	ds_read_b128 v[178:181], v189 offset:28672
	s_add_i32 m0, s45, 0x6000
	v_add_f32_e32 v131, v203, v131
	v_add_f32_e32 v130, v204, v130
	v_add_f32_e32 v131, v205, v131
	global_load_lds_dwordx4 v151, s[62:63]
	s_add_u32 s62, s62, 0x4000
	s_addc_u32 s63, s63, 0
	s_add_u32 s64, s64, 0x4000
	s_addc_u32 s65, s65, 0
	s_waitcnt lgkmcnt(6)
	v_mfma_f32_16x16x32_bf16 v[66:69], v[224:227], v[102:105], v[66:69]
	v_mfma_f32_16x16x32_bf16 v[82:85], v[224:227], v[118:121], v[82:85]
	ds_read_b128 v[224:227], v190 offset:16384
	v_add_f32_e32 v130, v206, v130
	v_add_f32_e32 v131, v207, v131
	v_add_f32_e32 v130, v130, v131
	v_mfma_f32_16x16x32_bf16 v[70:73], v[228:231], v[102:105], v[70:73]
	v_mfma_f32_16x16x32_bf16 v[86:89], v[228:231], v[118:121], v[86:89]
	ds_read_b128 v[228:231], v190 offset:20480
	v_add_f32_e32 v165, v165, v130
	v_add_f32_e32 v132, v208, v209
	v_add_f32_e32 v133, v210, v211
	s_waitcnt lgkmcnt(6)
	v_mfma_f32_16x16x32_bf16 v[74:77], v[232:235], v[102:105], v[74:77]
	v_mfma_f32_16x16x32_bf16 v[90:93], v[232:235], v[118:121], v[90:93]
	ds_read_b128 v[232:235], v190 offset:24576
	v_add_f32_e32 v132, v212, v132
	v_add_f32_e32 v133, v213, v133
	v_add_f32_e32 v132, v214, v132
	v_mfma_f32_16x16x32_bf16 v[78:81], v[236:239], v[102:105], v[78:81]
	v_mfma_f32_16x16x32_bf16 v[94:97], v[236:239], v[118:121], v[94:97]
	ds_read_b128 v[236:239], v190 offset:28672
	v_add_f32_e32 v133, v215, v133
	v_add_f32_e32 v132, v216, v132
	v_add_f32_e32 v133, v217, v133
	s_waitcnt lgkmcnt(6)
	v_mfma_f32_16x16x32_bf16 v[66:69], v[166:169], v[106:109], v[66:69]
	v_mfma_f32_16x16x32_bf16 v[82:85], v[166:169], v[122:125], v[82:85]
	ds_read_b64_tr_b16 v[166:167], v240 offset:32768
	ds_read_b64_tr_b16 v[168:169], v240 offset:36864
	v_add_f32_e32 v132, v218, v132
	v_add_f32_e32 v133, v219, v133
	v_add_f32_e32 v132, v220, v132
	v_mfma_f32_16x16x32_bf16 v[70:73], v[170:173], v[106:109], v[70:73]
	v_mfma_f32_16x16x32_bf16 v[86:89], v[170:173], v[122:125], v[86:89]
	ds_read_b64_tr_b16 v[170:171], v241 offset:32768
	ds_read_b64_tr_b16 v[172:173], v241 offset:36864
	v_add_f32_e32 v133, v221, v133
	v_add_f32_e32 v132, v222, v132
	v_add_f32_e32 v133, v223, v133
	s_waitcnt lgkmcnt(8)
	v_mfma_f32_16x16x32_bf16 v[74:77], v[174:177], v[106:109], v[74:77]
	v_mfma_f32_16x16x32_bf16 v[90:93], v[174:177], v[122:125], v[90:93]
	ds_read_b64_tr_b16 v[174:175], v242 offset:32768
	ds_read_b64_tr_b16 v[176:177], v242 offset:36864
	v_add_f32_e32 v132, v132, v133
	v_add_f32_e32 v163, v163, v132
	v_cvt_pk_bf16_f32 v192, v192, v193
	v_mfma_f32_16x16x32_bf16 v[78:81], v[178:181], v[106:109], v[78:81]
	v_mfma_f32_16x16x32_bf16 v[94:97], v[178:181], v[122:125], v[94:97]
	ds_read_b64_tr_b16 v[178:179], v243 offset:32768
	ds_read_b64_tr_b16 v[180:181], v243 offset:36864
	v_cvt_pk_bf16_f32 v193, v194, v195
	v_cvt_pk_bf16_f32 v194, v196, v197
	v_cvt_pk_bf16_f32 v195, v198, v199
	s_waitcnt lgkmcnt(10)
	v_mfma_f32_16x16x32_bf16 v[66:69], v[224:227], v[110:113], v[66:69]
	v_mfma_f32_16x16x32_bf16 v[82:85], v[224:227], v[126:129], v[82:85]
	ds_read_b64_tr_b16 v[224:225], v244 offset:32768
	ds_read_b64_tr_b16 v[226:227], v244 offset:36864
	v_cvt_pk_bf16_f32 v200, v200, v201
	v_cvt_pk_bf16_f32 v201, v202, v203
	v_cvt_pk_bf16_f32 v202, v204, v205
	v_mfma_f32_16x16x32_bf16 v[70:73], v[228:231], v[110:113], v[70:73]
	v_mfma_f32_16x16x32_bf16 v[86:89], v[228:231], v[126:129], v[86:89]
	v_cvt_pk_bf16_f32 v203, v206, v207
	v_cvt_pk_bf16_f32 v208, v208, v209
	v_cvt_pk_bf16_f32 v209, v210, v211
	s_waitcnt lgkmcnt(10)
	v_mfma_f32_16x16x32_bf16 v[74:77], v[232:235], v[110:113], v[74:77]
	v_mfma_f32_16x16x32_bf16 v[90:93], v[232:235], v[126:129], v[90:93]
	v_cvt_pk_bf16_f32 v210, v212, v213
	v_cvt_pk_bf16_f32 v211, v214, v215
	v_cvt_pk_bf16_f32 v216, v216, v217
	v_mfma_f32_16x16x32_bf16 v[78:81], v[236:239], v[110:113], v[78:81]
	v_mfma_f32_16x16x32_bf16 v[94:97], v[236:239], v[126:129], v[94:97]
	v_cvt_pk_bf16_f32 v217, v218, v219
	v_cvt_pk_bf16_f32 v218, v220, v221
	v_cvt_pk_bf16_f32 v219, v222, v223
	s_waitcnt lgkmcnt(6)
	v_mfma_f32_16x16x32_bf16 v[2:5], v[192:195], v[166:169], v[2:5]
	v_mfma_f32_16x16x32_bf16 v[34:37], v[208:211], v[166:169], v[34:37]
	ds_read_b64_tr_b16 v[228:229], v245 offset:32768
	ds_read_b64_tr_b16 v[230:231], v245 offset:36864
	v_mfma_f32_16x16x32_bf16 v[6:9], v[192:195], v[170:173], v[6:9]
	v_mfma_f32_16x16x32_bf16 v[38:41], v[208:211], v[170:173], v[38:41]
	ds_read_b64_tr_b16 v[232:233], v246 offset:32768
	ds_read_b64_tr_b16 v[234:235], v246 offset:36864
	s_waitcnt lgkmcnt(6)
	v_mfma_f32_16x16x32_bf16 v[10:13], v[192:195], v[174:177], v[10:13]
	v_mfma_f32_16x16x32_bf16 v[42:45], v[208:211], v[174:177], v[42:45]
	ds_read_b64_tr_b16 v[236:237], v247 offset:32768
	ds_read_b64_tr_b16 v[238:239], v247 offset:36864
	v_exp_f32_e32 v66, v66
	v_exp_f32_e32 v67, v67
	v_exp_f32_e32 v68, v68
	v_mfma_f32_16x16x32_bf16 v[14:17], v[192:195], v[178:181], v[14:17]
	v_mfma_f32_16x16x32_bf16 v[46:49], v[208:211], v[178:181], v[46:49]
	ds_read_b64_tr_b16 v[166:167], v240 offset:40960
	ds_read_b64_tr_b16 v[168:169], v240 offset:45056
	v_exp_f32_e32 v69, v69
	v_exp_f32_e32 v82, v82
	s_waitcnt lgkmcnt(6)
	v_mfma_f32_16x16x32_bf16 v[18:21], v[192:195], v[224:227], v[18:21]
	v_mfma_f32_16x16x32_bf16 v[50:53], v[208:211], v[224:227], v[50:53]
	ds_read_b64_tr_b16 v[170:171], v241 offset:40960
	ds_read_b64_tr_b16 v[172:173], v241 offset:45056
	v_exp_f32_e32 v83, v83
	v_exp_f32_e32 v84, v84
	v_mfma_f32_16x16x32_bf16 v[22:25], v[192:195], v[228:231], v[22:25]
	v_mfma_f32_16x16x32_bf16 v[54:57], v[208:211], v[228:231], v[54:57]
	ds_read_b64_tr_b16 v[174:175], v242 offset:40960
	ds_read_b64_tr_b16 v[176:177], v242 offset:45056
	v_exp_f32_e32 v85, v85
	v_exp_f32_e32 v70, v70
	v_exp_f32_e32 v71, v71
	s_waitcnt lgkmcnt(6)
	v_mfma_f32_16x16x32_bf16 v[26:29], v[192:195], v[232:235], v[26:29]
	v_mfma_f32_16x16x32_bf16 v[58:61], v[208:211], v[232:235], v[58:61]
	ds_read_b64_tr_b16 v[178:179], v243 offset:40960
	ds_read_b64_tr_b16 v[180:181], v243 offset:45056
	v_exp_f32_e32 v72, v72
	v_exp_f32_e32 v73, v73
	v_mfma_f32_16x16x32_bf16 v[30:33], v[192:195], v[236:239], v[30:33]
	v_mfma_f32_16x16x32_bf16 v[62:65], v[208:211], v[236:239], v[62:65]
	ds_read_b64_tr_b16 v[224:225], v244 offset:40960
	ds_read_b64_tr_b16 v[226:227], v244 offset:45056
	v_exp_f32_e32 v86, v86
	v_exp_f32_e32 v87, v87
	s_waitcnt lgkmcnt(6)
	v_mfma_f32_16x16x32_bf16 v[2:5], v[200:203], v[166:169], v[2:5]
	v_mfma_f32_16x16x32_bf16 v[34:37], v[216:219], v[166:169], v[34:37]
	ds_read_b64_tr_b16 v[228:229], v245 offset:40960
	ds_read_b64_tr_b16 v[230:231], v245 offset:45056
	ds_read_b128 v[166:169], v187 offset:49152
	v_exp_f32_e32 v88, v88
	v_exp_f32_e32 v89, v89
	v_mfma_f32_16x16x32_bf16 v[6:9], v[200:203], v[170:173], v[6:9]
	v_mfma_f32_16x16x32_bf16 v[38:41], v[216:219], v[170:173], v[38:41]
	ds_read_b64_tr_b16 v[232:233], v246 offset:40960
	ds_read_b64_tr_b16 v[234:235], v246 offset:45056
	ds_read_b128 v[170:173], v187 offset:53248
	v_exp_f32_e32 v74, v74
	v_exp_f32_e32 v75, v75
	v_exp_f32_e32 v76, v76
	s_waitcnt lgkmcnt(8)
	v_mfma_f32_16x16x32_bf16 v[10:13], v[200:203], v[174:177], v[10:13]
	v_mfma_f32_16x16x32_bf16 v[42:45], v[216:219], v[174:177], v[42:45]
	ds_read_b64_tr_b16 v[236:237], v247 offset:40960
	ds_read_b64_tr_b16 v[238:239], v247 offset:45056
	ds_read_b128 v[174:177], v187 offset:57344
	v_exp_f32_e32 v77, v77
	v_exp_f32_e32 v90, v90
	v_mfma_f32_16x16x32_bf16 v[14:17], v[200:203], v[178:181], v[14:17]
	v_mfma_f32_16x16x32_bf16 v[46:49], v[216:219], v[178:181], v[46:49]
	ds_read_b128 v[178:181], v187 offset:61440
	v_exp_f32_e32 v91, v91
	v_exp_f32_e32 v92, v92
	s_waitcnt lgkmcnt(8)
	v_mfma_f32_16x16x32_bf16 v[18:21], v[200:203], v[224:227], v[18:21]
	v_mfma_f32_16x16x32_bf16 v[50:53], v[216:219], v[224:227], v[50:53]
	ds_read_b128 v[224:227], v188 offset:49152
	v_exp_f32_e32 v93, v93
	v_exp_f32_e32 v78, v78
	v_exp_f32_e32 v79, v79
	v_mfma_f32_16x16x32_bf16 v[22:25], v[200:203], v[228:231], v[22:25]
	v_mfma_f32_16x16x32_bf16 v[54:57], v[216:219], v[228:231], v[54:57]
	ds_read_b128 v[228:231], v188 offset:53248
	v_exp_f32_e32 v80, v80
	v_exp_f32_e32 v81, v81
	s_waitcnt lgkmcnt(4)
	v_mfma_f32_16x16x32_bf16 v[26:29], v[200:203], v[232:235], v[26:29]
	v_mfma_f32_16x16x32_bf16 v[58:61], v[216:219], v[232:235], v[58:61]
	ds_read_b128 v[232:235], v188 offset:57344
	v_exp_f32_e32 v94, v94
	v_exp_f32_e32 v95, v95
	v_mfma_f32_16x16x32_bf16 v[30:33], v[200:203], v[236:239], v[30:33]
	v_mfma_f32_16x16x32_bf16 v[62:65], v[216:219], v[236:239], v[62:65]
	ds_read_b128 v[236:239], v188 offset:61440
	v_exp_f32_e32 v96, v96
	v_exp_f32_e32 v97, v97
	s_waitcnt vmcnt(0)
	s_barrier
	v_mfma_f32_16x16x32_bf16 v[192:195], v[166:169], v[98:101], 0
	v_mfma_f32_16x16x32_bf16 v[208:211], v[166:169], v[114:117], 0
	ds_read_b128 v[166:169], v189 offset:49152
	s_add_i32 m0, s45, 0x8000
	v_add_f32_e32 v130, v66, v67
	v_add_f32_e32 v131, v68, v69
	v_add_f32_e32 v130, v70, v130
	global_load_lds_dwordx4 v152, s[64:65]
	v_mfma_f32_16x16x32_bf16 v[196:199], v[170:173], v[98:101], 0
	v_mfma_f32_16x16x32_bf16 v[212:215], v[170:173], v[114:117], 0
	ds_read_b128 v[170:173], v189 offset:53248
	s_add_i32 m0, s45, 0xc000
	v_add_f32_e32 v131, v71, v131
	v_add_f32_e32 v130, v72, v130
	v_add_f32_e32 v131, v73, v131
	global_load_lds_dwordx4 v150, s[62:63]
	s_waitcnt lgkmcnt(6)
	v_mfma_f32_16x16x32_bf16 v[200:203], v[174:177], v[98:101], 0
	v_mfma_f32_16x16x32_bf16 v[216:219], v[174:177], v[114:117], 0
	ds_read_b128 v[174:177], v189 offset:57344
	s_add_i32 m0, s45, 0xa000
	v_add_f32_e32 v130, v74, v130
	v_add_f32_e32 v131, v75, v131
	v_add_f32_e32 v130, v76, v130
	global_load_lds_dwordx4 v153, s[64:65]
	v_mfma_f32_16x16x32_bf16 v[204:207], v[178:181], v[98:101], 0
	v_mfma_f32_16x16x32_bf16 v[220:223], v[178:181], v[114:117], 0
	ds_read_b128 v[178:181], v189 offset:61440
	s_add_i32 m0, s45, 0xe000
	v_add_f32_e32 v131, v77, v131
	v_add_f32_e32 v130, v78, v130
	v_add_f32_e32 v131, v79, v131
	global_load_lds_dwordx4 v151, s[62:63]
	s_add_u32 s62, s62, 0x4000
	s_addc_u32 s63, s63, 0
	s_add_u32 s64, s64, 0x4000
	s_addc_u32 s65, s65, 0
	s_waitcnt lgkmcnt(6)
	v_mfma_f32_16x16x32_bf16 v[192:195], v[224:227], v[102:105], v[192:195]
	v_mfma_f32_16x16x32_bf16 v[208:211], v[224:227], v[118:121], v[208:211]
	ds_read_b128 v[224:227], v190 offset:49152
	v_add_f32_e32 v130, v80, v130
	v_add_f32_e32 v131, v81, v131
	v_add_f32_e32 v130, v130, v131
	v_mfma_f32_16x16x32_bf16 v[196:199], v[228:231], v[102:105], v[196:199]
	v_mfma_f32_16x16x32_bf16 v[212:215], v[228:231], v[118:121], v[212:215]
	ds_read_b128 v[228:231], v190 offset:53248
	v_add_f32_e32 v165, v165, v130
	v_add_f32_e32 v132, v82, v83
	v_add_f32_e32 v133, v84, v85
	s_waitcnt lgkmcnt(6)
	v_mfma_f32_16x16x32_bf16 v[200:203], v[232:235], v[102:105], v[200:203]
	v_mfma_f32_16x16x32_bf16 v[216:219], v[232:235], v[118:121], v[216:219]
	ds_read_b128 v[232:235], v190 offset:57344
	v_add_f32_e32 v132, v86, v132
	v_add_f32_e32 v133, v87, v133
	v_add_f32_e32 v132, v88, v132
	v_mfma_f32_16x16x32_bf16 v[204:207], v[236:239], v[102:105], v[204:207]
	v_mfma_f32_16x16x32_bf16 v[220:223], v[236:239], v[118:121], v[220:223]
	ds_read_b128 v[236:239], v190 offset:61440
	v_add_f32_e32 v133, v89, v133
	v_add_f32_e32 v132, v90, v132
	v_add_f32_e32 v133, v91, v133
	s_waitcnt lgkmcnt(6)
	v_mfma_f32_16x16x32_bf16 v[192:195], v[166:169], v[106:109], v[192:195]
	v_mfma_f32_16x16x32_bf16 v[208:211], v[166:169], v[122:125], v[208:211]
	ds_read_b64_tr_b16 v[166:167], v142 offset:0
	ds_read_b64_tr_b16 v[168:169], v142 offset:4096
	v_add_f32_e32 v132, v92, v132
	v_add_f32_e32 v133, v93, v133
	v_add_f32_e32 v132, v94, v132
	v_mfma_f32_16x16x32_bf16 v[196:199], v[170:173], v[106:109], v[196:199]
	v_mfma_f32_16x16x32_bf16 v[212:215], v[170:173], v[122:125], v[212:215]
	ds_read_b64_tr_b16 v[170:171], v143 offset:0
	ds_read_b64_tr_b16 v[172:173], v143 offset:4096
	v_add_f32_e32 v133, v95, v133
	v_add_f32_e32 v132, v96, v132
	v_add_f32_e32 v133, v97, v133
	s_waitcnt lgkmcnt(8)
	v_mfma_f32_16x16x32_bf16 v[200:203], v[174:177], v[106:109], v[200:203]
	v_mfma_f32_16x16x32_bf16 v[216:219], v[174:177], v[122:125], v[216:219]
	ds_read_b64_tr_b16 v[174:175], v144 offset:0
	ds_read_b64_tr_b16 v[176:177], v144 offset:4096
	v_add_f32_e32 v132, v132, v133
	v_add_f32_e32 v163, v163, v132
	v_cvt_pk_bf16_f32 v66, v66, v67
	v_mfma_f32_16x16x32_bf16 v[204:207], v[178:181], v[106:109], v[204:207]
	v_mfma_f32_16x16x32_bf16 v[220:223], v[178:181], v[122:125], v[220:223]
	ds_read_b64_tr_b16 v[178:179], v145 offset:0
	ds_read_b64_tr_b16 v[180:181], v145 offset:4096
	v_cvt_pk_bf16_f32 v67, v68, v69
	v_cvt_pk_bf16_f32 v68, v70, v71
	v_cvt_pk_bf16_f32 v69, v72, v73
	s_waitcnt lgkmcnt(10)
	v_mfma_f32_16x16x32_bf16 v[192:195], v[224:227], v[110:113], v[192:195]
	v_mfma_f32_16x16x32_bf16 v[208:211], v[224:227], v[126:129], v[208:211]
	ds_read_b64_tr_b16 v[224:225], v146 offset:0
	ds_read_b64_tr_b16 v[226:227], v146 offset:4096
	v_cvt_pk_bf16_f32 v74, v74, v75
	v_cvt_pk_bf16_f32 v75, v76, v77
	v_cvt_pk_bf16_f32 v76, v78, v79
	v_mfma_f32_16x16x32_bf16 v[196:199], v[228:231], v[110:113], v[196:199]
	v_mfma_f32_16x16x32_bf16 v[212:215], v[228:231], v[126:129], v[212:215]
	v_cvt_pk_bf16_f32 v77, v80, v81
	v_cvt_pk_bf16_f32 v82, v82, v83
	v_cvt_pk_bf16_f32 v83, v84, v85
	s_waitcnt lgkmcnt(10)
	v_mfma_f32_16x16x32_bf16 v[200:203], v[232:235], v[110:113], v[200:203]
	v_mfma_f32_16x16x32_bf16 v[216:219], v[232:235], v[126:129], v[216:219]
	v_cvt_pk_bf16_f32 v84, v86, v87
	v_cvt_pk_bf16_f32 v85, v88, v89
	v_cvt_pk_bf16_f32 v90, v90, v91
	v_mfma_f32_16x16x32_bf16 v[204:207], v[236:239], v[110:113], v[204:207]
	v_mfma_f32_16x16x32_bf16 v[220:223], v[236:239], v[126:129], v[220:223]
	v_cvt_pk_bf16_f32 v91, v92, v93
	v_cvt_pk_bf16_f32 v92, v94, v95
	v_cvt_pk_bf16_f32 v93, v96, v97
	s_waitcnt lgkmcnt(6)
	v_mfma_f32_16x16x32_bf16 v[2:5], v[66:69], v[166:169], v[2:5]
	v_mfma_f32_16x16x32_bf16 v[34:37], v[82:85], v[166:169], v[34:37]
	ds_read_b64_tr_b16 v[228:229], v147 offset:0
	ds_read_b64_tr_b16 v[230:231], v147 offset:4096
	v_mfma_f32_16x16x32_bf16 v[6:9], v[66:69], v[170:173], v[6:9]
	v_mfma_f32_16x16x32_bf16 v[38:41], v[82:85], v[170:173], v[38:41]
	ds_read_b64_tr_b16 v[232:233], v148 offset:0
	ds_read_b64_tr_b16 v[234:235], v148 offset:4096
	s_waitcnt lgkmcnt(6)
	v_mfma_f32_16x16x32_bf16 v[10:13], v[66:69], v[174:177], v[10:13]
	v_mfma_f32_16x16x32_bf16 v[42:45], v[82:85], v[174:177], v[42:45]
	ds_read_b64_tr_b16 v[236:237], v149 offset:0
	ds_read_b64_tr_b16 v[238:239], v149 offset:4096
	v_exp_f32_e32 v192, v192
	v_exp_f32_e32 v193, v193
	v_exp_f32_e32 v194, v194
	v_mfma_f32_16x16x32_bf16 v[14:17], v[66:69], v[178:181], v[14:17]
	v_mfma_f32_16x16x32_bf16 v[46:49], v[82:85], v[178:181], v[46:49]
	ds_read_b64_tr_b16 v[166:167], v142 offset:8192
	ds_read_b64_tr_b16 v[168:169], v142 offset:12288
	v_exp_f32_e32 v195, v195
	v_exp_f32_e32 v208, v208
	s_waitcnt lgkmcnt(6)
	v_mfma_f32_16x16x32_bf16 v[18:21], v[66:69], v[224:227], v[18:21]
	v_mfma_f32_16x16x32_bf16 v[50:53], v[82:85], v[224:227], v[50:53]
	ds_read_b64_tr_b16 v[170:171], v143 offset:8192
	ds_read_b64_tr_b16 v[172:173], v143 offset:12288
	v_exp_f32_e32 v209, v209
	v_exp_f32_e32 v210, v210
	v_mfma_f32_16x16x32_bf16 v[22:25], v[66:69], v[228:231], v[22:25]
	v_mfma_f32_16x16x32_bf16 v[54:57], v[82:85], v[228:231], v[54:57]
	ds_read_b64_tr_b16 v[174:175], v144 offset:8192
	ds_read_b64_tr_b16 v[176:177], v144 offset:12288
	v_exp_f32_e32 v211, v211
	v_exp_f32_e32 v196, v196
	v_exp_f32_e32 v197, v197
	s_waitcnt lgkmcnt(6)
	v_mfma_f32_16x16x32_bf16 v[26:29], v[66:69], v[232:235], v[26:29]
	v_mfma_f32_16x16x32_bf16 v[58:61], v[82:85], v[232:235], v[58:61]
	ds_read_b64_tr_b16 v[178:179], v145 offset:8192
	ds_read_b64_tr_b16 v[180:181], v145 offset:12288
	v_exp_f32_e32 v198, v198
	v_exp_f32_e32 v199, v199
	v_mfma_f32_16x16x32_bf16 v[30:33], v[66:69], v[236:239], v[30:33]
	v_mfma_f32_16x16x32_bf16 v[62:65], v[82:85], v[236:239], v[62:65]
	ds_read_b64_tr_b16 v[224:225], v146 offset:8192
	ds_read_b64_tr_b16 v[226:227], v146 offset:12288
	v_exp_f32_e32 v212, v212
	v_exp_f32_e32 v213, v213
	s_waitcnt lgkmcnt(6)
	v_mfma_f32_16x16x32_bf16 v[2:5], v[74:77], v[166:169], v[2:5]
	v_mfma_f32_16x16x32_bf16 v[34:37], v[90:93], v[166:169], v[34:37]
	ds_read_b64_tr_b16 v[228:229], v147 offset:8192
	ds_read_b64_tr_b16 v[230:231], v147 offset:12288
	ds_read_b128 v[166:169], v183 offset:16384
	v_exp_f32_e32 v214, v214
	v_exp_f32_e32 v215, v215
	v_mfma_f32_16x16x32_bf16 v[6:9], v[74:77], v[170:173], v[6:9]
	v_mfma_f32_16x16x32_bf16 v[38:41], v[90:93], v[170:173], v[38:41]
	ds_read_b64_tr_b16 v[232:233], v148 offset:8192
	ds_read_b64_tr_b16 v[234:235], v148 offset:12288
	ds_read_b128 v[170:173], v183 offset:20480
	v_exp_f32_e32 v200, v200
	v_exp_f32_e32 v201, v201
	v_exp_f32_e32 v202, v202
	s_waitcnt lgkmcnt(8)
	v_mfma_f32_16x16x32_bf16 v[10:13], v[74:77], v[174:177], v[10:13]
	v_mfma_f32_16x16x32_bf16 v[42:45], v[90:93], v[174:177], v[42:45]
	ds_read_b64_tr_b16 v[236:237], v149 offset:8192
	ds_read_b64_tr_b16 v[238:239], v149 offset:12288
	ds_read_b128 v[174:177], v183 offset:24576
	v_exp_f32_e32 v203, v203
	v_exp_f32_e32 v216, v216
	v_mfma_f32_16x16x32_bf16 v[14:17], v[74:77], v[178:181], v[14:17]
	v_mfma_f32_16x16x32_bf16 v[46:49], v[90:93], v[178:181], v[46:49]
	ds_read_b128 v[178:181], v183 offset:28672
	v_exp_f32_e32 v217, v217
	v_exp_f32_e32 v218, v218
	s_waitcnt lgkmcnt(8)
	v_mfma_f32_16x16x32_bf16 v[18:21], v[74:77], v[224:227], v[18:21]
	v_mfma_f32_16x16x32_bf16 v[50:53], v[90:93], v[224:227], v[50:53]
	ds_read_b128 v[224:227], v184 offset:16384
	v_exp_f32_e32 v219, v219
	v_exp_f32_e32 v204, v204
	v_exp_f32_e32 v205, v205
	v_mfma_f32_16x16x32_bf16 v[22:25], v[74:77], v[228:231], v[22:25]
	v_mfma_f32_16x16x32_bf16 v[54:57], v[90:93], v[228:231], v[54:57]
	ds_read_b128 v[228:231], v184 offset:20480
	v_exp_f32_e32 v206, v206
	v_exp_f32_e32 v207, v207
	s_waitcnt lgkmcnt(4)
	v_mfma_f32_16x16x32_bf16 v[26:29], v[74:77], v[232:235], v[26:29]
	v_mfma_f32_16x16x32_bf16 v[58:61], v[90:93], v[232:235], v[58:61]
	ds_read_b128 v[232:235], v184 offset:24576
	v_exp_f32_e32 v220, v220
	v_exp_f32_e32 v221, v221
	v_mfma_f32_16x16x32_bf16 v[30:33], v[74:77], v[236:239], v[30:33]
	v_mfma_f32_16x16x32_bf16 v[62:65], v[90:93], v[236:239], v[62:65]
	ds_read_b128 v[236:239], v184 offset:28672
	v_exp_f32_e32 v222, v222
	v_exp_f32_e32 v223, v223
	s_waitcnt vmcnt(0)
	s_barrier
	v_mfma_f32_16x16x32_bf16 v[66:69], v[166:169], v[98:101], 0
	v_mfma_f32_16x16x32_bf16 v[82:85], v[166:169], v[114:117], 0
	ds_read_b128 v[166:169], v185 offset:16384
	s_add_i32 m0, s45, 0x10000
	v_add_f32_e32 v130, v192, v193
	v_add_f32_e32 v131, v194, v195
	v_add_f32_e32 v130, v196, v130
	global_load_lds_dwordx4 v152, s[64:65]
	v_mfma_f32_16x16x32_bf16 v[70:73], v[170:173], v[98:101], 0
	v_mfma_f32_16x16x32_bf16 v[86:89], v[170:173], v[114:117], 0
	ds_read_b128 v[170:173], v185 offset:20480
	s_add_i32 m0, s45, 0x14000
	v_add_f32_e32 v131, v197, v131
	v_add_f32_e32 v130, v198, v130
	v_add_f32_e32 v131, v199, v131
	global_load_lds_dwordx4 v150, s[62:63]
	s_waitcnt lgkmcnt(6)
	v_mfma_f32_16x16x32_bf16 v[74:77], v[174:177], v[98:101], 0
	v_mfma_f32_16x16x32_bf16 v[90:93], v[174:177], v[114:117], 0
	ds_read_b128 v[174:177], v185 offset:24576
	s_add_i32 m0, s45, 0x12000
	v_add_f32_e32 v130, v200, v130
	v_add_f32_e32 v131, v201, v131
	v_add_f32_e32 v130, v202, v130
	global_load_lds_dwordx4 v153, s[64:65]
	v_mfma_f32_16x16x32_bf16 v[78:81], v[178:181], v[98:101], 0
	v_mfma_f32_16x16x32_bf16 v[94:97], v[178:181], v[114:117], 0
	ds_read_b128 v[178:181], v185 offset:28672
	s_add_i32 m0, s45, 0x16000
	v_add_f32_e32 v131, v203, v131
	v_add_f32_e32 v130, v204, v130
	v_add_f32_e32 v131, v205, v131
	global_load_lds_dwordx4 v151, s[62:63]
	s_add_u32 s62, s62, 0x4000
	s_addc_u32 s63, s63, 0
	s_add_u32 s64, s64, 0x4000
	s_addc_u32 s65, s65, 0
	s_waitcnt lgkmcnt(6)
	v_mfma_f32_16x16x32_bf16 v[66:69], v[224:227], v[102:105], v[66:69]
	v_mfma_f32_16x16x32_bf16 v[82:85], v[224:227], v[118:121], v[82:85]
	ds_read_b128 v[224:227], v186 offset:16384
	v_add_f32_e32 v130, v206, v130
	v_add_f32_e32 v131, v207, v131
	v_add_f32_e32 v130, v130, v131
	v_mfma_f32_16x16x32_bf16 v[70:73], v[228:231], v[102:105], v[70:73]
	v_mfma_f32_16x16x32_bf16 v[86:89], v[228:231], v[118:121], v[86:89]
	ds_read_b128 v[228:231], v186 offset:20480
	v_add_f32_e32 v165, v165, v130
	v_add_f32_e32 v132, v208, v209
	v_add_f32_e32 v133, v210, v211
	s_waitcnt lgkmcnt(6)
	v_mfma_f32_16x16x32_bf16 v[74:77], v[232:235], v[102:105], v[74:77]
	v_mfma_f32_16x16x32_bf16 v[90:93], v[232:235], v[118:121], v[90:93]
	ds_read_b128 v[232:235], v186 offset:24576
	v_add_f32_e32 v132, v212, v132
	v_add_f32_e32 v133, v213, v133
	v_add_f32_e32 v132, v214, v132
	v_mfma_f32_16x16x32_bf16 v[78:81], v[236:239], v[102:105], v[78:81]
	v_mfma_f32_16x16x32_bf16 v[94:97], v[236:239], v[118:121], v[94:97]
	ds_read_b128 v[236:239], v186 offset:28672
	v_add_f32_e32 v133, v215, v133
	v_add_f32_e32 v132, v216, v132
	v_add_f32_e32 v133, v217, v133
	s_waitcnt lgkmcnt(6)
	v_mfma_f32_16x16x32_bf16 v[66:69], v[166:169], v[106:109], v[66:69]
	v_mfma_f32_16x16x32_bf16 v[82:85], v[166:169], v[122:125], v[82:85]
	ds_read_b64_tr_b16 v[166:167], v142 offset:32768
	ds_read_b64_tr_b16 v[168:169], v142 offset:36864
	v_add_f32_e32 v132, v218, v132
	v_add_f32_e32 v133, v219, v133
	v_add_f32_e32 v132, v220, v132
	v_mfma_f32_16x16x32_bf16 v[70:73], v[170:173], v[106:109], v[70:73]
	v_mfma_f32_16x16x32_bf16 v[86:89], v[170:173], v[122:125], v[86:89]
	ds_read_b64_tr_b16 v[170:171], v143 offset:32768
	ds_read_b64_tr_b16 v[172:173], v143 offset:36864
	v_add_f32_e32 v133, v221, v133
	v_add_f32_e32 v132, v222, v132
	v_add_f32_e32 v133, v223, v133
	s_waitcnt lgkmcnt(8)
	v_mfma_f32_16x16x32_bf16 v[74:77], v[174:177], v[106:109], v[74:77]
	v_mfma_f32_16x16x32_bf16 v[90:93], v[174:177], v[122:125], v[90:93]
	ds_read_b64_tr_b16 v[174:175], v144 offset:32768
	ds_read_b64_tr_b16 v[176:177], v144 offset:36864
	v_add_f32_e32 v132, v132, v133
	v_add_f32_e32 v163, v163, v132
	v_cvt_pk_bf16_f32 v192, v192, v193
	v_mfma_f32_16x16x32_bf16 v[78:81], v[178:181], v[106:109], v[78:81]
	v_mfma_f32_16x16x32_bf16 v[94:97], v[178:181], v[122:125], v[94:97]
	ds_read_b64_tr_b16 v[178:179], v145 offset:32768
	ds_read_b64_tr_b16 v[180:181], v145 offset:36864
	v_cvt_pk_bf16_f32 v193, v194, v195
	v_cvt_pk_bf16_f32 v194, v196, v197
	v_cvt_pk_bf16_f32 v195, v198, v199
	s_waitcnt lgkmcnt(10)
	v_mfma_f32_16x16x32_bf16 v[66:69], v[224:227], v[110:113], v[66:69]
	v_mfma_f32_16x16x32_bf16 v[82:85], v[224:227], v[126:129], v[82:85]
	ds_read_b64_tr_b16 v[224:225], v146 offset:32768
	ds_read_b64_tr_b16 v[226:227], v146 offset:36864
	v_cvt_pk_bf16_f32 v200, v200, v201
	v_cvt_pk_bf16_f32 v201, v202, v203
	v_cvt_pk_bf16_f32 v202, v204, v205
	v_mfma_f32_16x16x32_bf16 v[70:73], v[228:231], v[110:113], v[70:73]
	v_mfma_f32_16x16x32_bf16 v[86:89], v[228:231], v[126:129], v[86:89]
	v_cvt_pk_bf16_f32 v203, v206, v207
	v_cvt_pk_bf16_f32 v208, v208, v209
	v_cvt_pk_bf16_f32 v209, v210, v211
	s_waitcnt lgkmcnt(10)
	v_mfma_f32_16x16x32_bf16 v[74:77], v[232:235], v[110:113], v[74:77]
	v_mfma_f32_16x16x32_bf16 v[90:93], v[232:235], v[126:129], v[90:93]
	v_cvt_pk_bf16_f32 v210, v212, v213
	v_cvt_pk_bf16_f32 v211, v214, v215
	v_cvt_pk_bf16_f32 v216, v216, v217
	v_mfma_f32_16x16x32_bf16 v[78:81], v[236:239], v[110:113], v[78:81]
	v_mfma_f32_16x16x32_bf16 v[94:97], v[236:239], v[126:129], v[94:97]
	v_cvt_pk_bf16_f32 v217, v218, v219
	v_cvt_pk_bf16_f32 v218, v220, v221
	v_cvt_pk_bf16_f32 v219, v222, v223
	s_waitcnt lgkmcnt(6)
	v_mfma_f32_16x16x32_bf16 v[2:5], v[192:195], v[166:169], v[2:5]
	v_mfma_f32_16x16x32_bf16 v[34:37], v[208:211], v[166:169], v[34:37]
	ds_read_b64_tr_b16 v[228:229], v147 offset:32768
	ds_read_b64_tr_b16 v[230:231], v147 offset:36864
	v_mfma_f32_16x16x32_bf16 v[6:9], v[192:195], v[170:173], v[6:9]
	v_mfma_f32_16x16x32_bf16 v[38:41], v[208:211], v[170:173], v[38:41]
	ds_read_b64_tr_b16 v[232:233], v148 offset:32768
	ds_read_b64_tr_b16 v[234:235], v148 offset:36864
	s_waitcnt lgkmcnt(6)
	v_mfma_f32_16x16x32_bf16 v[10:13], v[192:195], v[174:177], v[10:13]
	v_mfma_f32_16x16x32_bf16 v[42:45], v[208:211], v[174:177], v[42:45]
	ds_read_b64_tr_b16 v[236:237], v149 offset:32768
	ds_read_b64_tr_b16 v[238:239], v149 offset:36864
	v_exp_f32_e32 v66, v66
	v_exp_f32_e32 v67, v67
	v_exp_f32_e32 v68, v68
	v_mfma_f32_16x16x32_bf16 v[14:17], v[192:195], v[178:181], v[14:17]
	v_mfma_f32_16x16x32_bf16 v[46:49], v[208:211], v[178:181], v[46:49]
	ds_read_b64_tr_b16 v[166:167], v142 offset:40960
	ds_read_b64_tr_b16 v[168:169], v142 offset:45056
	v_exp_f32_e32 v69, v69
	v_exp_f32_e32 v82, v82
	s_waitcnt lgkmcnt(6)
	v_mfma_f32_16x16x32_bf16 v[18:21], v[192:195], v[224:227], v[18:21]
	v_mfma_f32_16x16x32_bf16 v[50:53], v[208:211], v[224:227], v[50:53]
	ds_read_b64_tr_b16 v[170:171], v143 offset:40960
	ds_read_b64_tr_b16 v[172:173], v143 offset:45056
	v_exp_f32_e32 v83, v83
	v_exp_f32_e32 v84, v84
	v_mfma_f32_16x16x32_bf16 v[22:25], v[192:195], v[228:231], v[22:25]
	v_mfma_f32_16x16x32_bf16 v[54:57], v[208:211], v[228:231], v[54:57]
	ds_read_b64_tr_b16 v[174:175], v144 offset:40960
	ds_read_b64_tr_b16 v[176:177], v144 offset:45056
	v_exp_f32_e32 v85, v85
	v_exp_f32_e32 v70, v70
	v_exp_f32_e32 v71, v71
	s_waitcnt lgkmcnt(6)
	v_mfma_f32_16x16x32_bf16 v[26:29], v[192:195], v[232:235], v[26:29]
	v_mfma_f32_16x16x32_bf16 v[58:61], v[208:211], v[232:235], v[58:61]
	ds_read_b64_tr_b16 v[178:179], v145 offset:40960
	ds_read_b64_tr_b16 v[180:181], v145 offset:45056
	v_exp_f32_e32 v72, v72
	v_exp_f32_e32 v73, v73
	v_mfma_f32_16x16x32_bf16 v[30:33], v[192:195], v[236:239], v[30:33]
	v_mfma_f32_16x16x32_bf16 v[62:65], v[208:211], v[236:239], v[62:65]
	ds_read_b64_tr_b16 v[224:225], v146 offset:40960
	ds_read_b64_tr_b16 v[226:227], v146 offset:45056
	v_exp_f32_e32 v86, v86
	v_exp_f32_e32 v87, v87
	s_waitcnt lgkmcnt(6)
	v_mfma_f32_16x16x32_bf16 v[2:5], v[200:203], v[166:169], v[2:5]
	v_mfma_f32_16x16x32_bf16 v[34:37], v[216:219], v[166:169], v[34:37]
	ds_read_b64_tr_b16 v[228:229], v147 offset:40960
	ds_read_b64_tr_b16 v[230:231], v147 offset:45056
	ds_read_b128 v[166:169], v183 offset:49152
	v_exp_f32_e32 v88, v88
	v_exp_f32_e32 v89, v89
	v_mfma_f32_16x16x32_bf16 v[6:9], v[200:203], v[170:173], v[6:9]
	v_mfma_f32_16x16x32_bf16 v[38:41], v[216:219], v[170:173], v[38:41]
	ds_read_b64_tr_b16 v[232:233], v148 offset:40960
	ds_read_b64_tr_b16 v[234:235], v148 offset:45056
	ds_read_b128 v[170:173], v183 offset:53248
	v_exp_f32_e32 v74, v74
	v_exp_f32_e32 v75, v75
	v_exp_f32_e32 v76, v76
	s_waitcnt lgkmcnt(8)
	v_mfma_f32_16x16x32_bf16 v[10:13], v[200:203], v[174:177], v[10:13]
	v_mfma_f32_16x16x32_bf16 v[42:45], v[216:219], v[174:177], v[42:45]
	ds_read_b64_tr_b16 v[236:237], v149 offset:40960
	ds_read_b64_tr_b16 v[238:239], v149 offset:45056
	ds_read_b128 v[174:177], v183 offset:57344
	v_exp_f32_e32 v77, v77
	v_exp_f32_e32 v90, v90
	v_mfma_f32_16x16x32_bf16 v[14:17], v[200:203], v[178:181], v[14:17]
	v_mfma_f32_16x16x32_bf16 v[46:49], v[216:219], v[178:181], v[46:49]
	ds_read_b128 v[178:181], v183 offset:61440
	v_exp_f32_e32 v91, v91
	v_exp_f32_e32 v92, v92
	s_waitcnt lgkmcnt(8)
	v_mfma_f32_16x16x32_bf16 v[18:21], v[200:203], v[224:227], v[18:21]
	v_mfma_f32_16x16x32_bf16 v[50:53], v[216:219], v[224:227], v[50:53]
	ds_read_b128 v[224:227], v184 offset:49152
	v_exp_f32_e32 v93, v93
	v_exp_f32_e32 v78, v78
	v_exp_f32_e32 v79, v79
	v_mfma_f32_16x16x32_bf16 v[22:25], v[200:203], v[228:231], v[22:25]
	v_mfma_f32_16x16x32_bf16 v[54:57], v[216:219], v[228:231], v[54:57]
	ds_read_b128 v[228:231], v184 offset:53248
	v_exp_f32_e32 v80, v80
	v_exp_f32_e32 v81, v81
	s_waitcnt lgkmcnt(4)
	v_mfma_f32_16x16x32_bf16 v[26:29], v[200:203], v[232:235], v[26:29]
	v_mfma_f32_16x16x32_bf16 v[58:61], v[216:219], v[232:235], v[58:61]
	ds_read_b128 v[232:235], v184 offset:57344
	v_exp_f32_e32 v94, v94
	v_exp_f32_e32 v95, v95
	v_mfma_f32_16x16x32_bf16 v[30:33], v[200:203], v[236:239], v[30:33]
	v_mfma_f32_16x16x32_bf16 v[62:65], v[216:219], v[236:239], v[62:65]
	ds_read_b128 v[236:239], v184 offset:61440
	v_exp_f32_e32 v96, v96
	v_exp_f32_e32 v97, v97
	s_waitcnt vmcnt(0)
	s_barrier
	s_sub_u32 s66, s66, 1
	s_cmp_lg_u32 s66, 0
	s_cbranch_scc1 .Lattn_loop
	v_mfma_f32_16x16x32_bf16 v[192:195], v[166:169], v[98:101], 0
	v_mfma_f32_16x16x32_bf16 v[208:211], v[166:169], v[114:117], 0
	ds_read_b128 v[166:169], v185 offset:49152
	s_add_i32 m0, s45, 0x18000
	v_add_f32_e32 v130, v66, v67
	v_add_f32_e32 v131, v68, v69
	v_add_f32_e32 v130, v70, v130
	global_load_lds_dwordx4 v152, s[64:65]
	v_mfma_f32_16x16x32_bf16 v[196:199], v[170:173], v[98:101], 0
	v_mfma_f32_16x16x32_bf16 v[212:215], v[170:173], v[114:117], 0
	ds_read_b128 v[170:173], v185 offset:53248
	s_add_i32 m0, s45, 0x1c000
	v_add_f32_e32 v131, v71, v131
	v_add_f32_e32 v130, v72, v130
	v_add_f32_e32 v131, v73, v131
	global_load_lds_dwordx4 v150, s[62:63]
	s_waitcnt lgkmcnt(6)
	v_mfma_f32_16x16x32_bf16 v[200:203], v[174:177], v[98:101], 0
	v_mfma_f32_16x16x32_bf16 v[216:219], v[174:177], v[114:117], 0
	ds_read_b128 v[174:177], v185 offset:57344
	s_add_i32 m0, s45, 0x1a000
	v_add_f32_e32 v130, v74, v130
	v_add_f32_e32 v131, v75, v131
	v_add_f32_e32 v130, v76, v130
	global_load_lds_dwordx4 v153, s[64:65]
	v_mfma_f32_16x16x32_bf16 v[204:207], v[178:181], v[98:101], 0
	v_mfma_f32_16x16x32_bf16 v[220:223], v[178:181], v[114:117], 0
	ds_read_b128 v[178:181], v185 offset:61440
	s_add_i32 m0, s45, 0x1e000
	v_add_f32_e32 v131, v77, v131
	v_add_f32_e32 v130, v78, v130
	v_add_f32_e32 v131, v79, v131
	global_load_lds_dwordx4 v151, s[62:63]
	s_add_u32 s62, s62, 0x4000
	s_addc_u32 s63, s63, 0
	s_add_u32 s64, s64, 0x4000
	s_addc_u32 s65, s65, 0
	s_waitcnt lgkmcnt(6)
	v_mfma_f32_16x16x32_bf16 v[192:195], v[224:227], v[102:105], v[192:195]
	v_mfma_f32_16x16x32_bf16 v[208:211], v[224:227], v[118:121], v[208:211]
	ds_read_b128 v[224:227], v186 offset:49152
	v_add_f32_e32 v130, v80, v130
	v_add_f32_e32 v131, v81, v131
	v_add_f32_e32 v130, v130, v131
	v_mfma_f32_16x16x32_bf16 v[196:199], v[228:231], v[102:105], v[196:199]
	v_mfma_f32_16x16x32_bf16 v[212:215], v[228:231], v[118:121], v[212:215]
	ds_read_b128 v[228:231], v186 offset:53248
	v_add_f32_e32 v165, v165, v130
	v_add_f32_e32 v132, v82, v83
	v_add_f32_e32 v133, v84, v85
	s_waitcnt lgkmcnt(6)
	v_mfma_f32_16x16x32_bf16 v[200:203], v[232:235], v[102:105], v[200:203]
	v_mfma_f32_16x16x32_bf16 v[216:219], v[232:235], v[118:121], v[216:219]
	ds_read_b128 v[232:235], v186 offset:57344
	v_add_f32_e32 v132, v86, v132
	v_add_f32_e32 v133, v87, v133
	v_add_f32_e32 v132, v88, v132
	v_mfma_f32_16x16x32_bf16 v[204:207], v[236:239], v[102:105], v[204:207]
	v_mfma_f32_16x16x32_bf16 v[220:223], v[236:239], v[118:121], v[220:223]
	ds_read_b128 v[236:239], v186 offset:61440
	v_add_f32_e32 v133, v89, v133
	v_add_f32_e32 v132, v90, v132
	v_add_f32_e32 v133, v91, v133
	s_waitcnt lgkmcnt(6)
	v_mfma_f32_16x16x32_bf16 v[192:195], v[166:169], v[106:109], v[192:195]
	v_mfma_f32_16x16x32_bf16 v[208:211], v[166:169], v[122:125], v[208:211]
	ds_read_b64_tr_b16 v[166:167], v240 offset:0
	ds_read_b64_tr_b16 v[168:169], v240 offset:4096
	v_add_f32_e32 v132, v92, v132
	v_add_f32_e32 v133, v93, v133
	v_add_f32_e32 v132, v94, v132
	v_mfma_f32_16x16x32_bf16 v[196:199], v[170:173], v[106:109], v[196:199]
	v_mfma_f32_16x16x32_bf16 v[212:215], v[170:173], v[122:125], v[212:215]
	ds_read_b64_tr_b16 v[170:171], v241 offset:0
	ds_read_b64_tr_b16 v[172:173], v241 offset:4096
	v_add_f32_e32 v133, v95, v133
	v_add_f32_e32 v132, v96, v132
	v_add_f32_e32 v133, v97, v133
	s_waitcnt lgkmcnt(8)
	v_mfma_f32_16x16x32_bf16 v[200:203], v[174:177], v[106:109], v[200:203]
	v_mfma_f32_16x16x32_bf16 v[216:219], v[174:177], v[122:125], v[216:219]
	ds_read_b64_tr_b16 v[174:175], v242 offset:0
	ds_read_b64_tr_b16 v[176:177], v242 offset:4096
	v_add_f32_e32 v132, v132, v133
	v_add_f32_e32 v163, v163, v132
	v_cvt_pk_bf16_f32 v66, v66, v67
	v_mfma_f32_16x16x32_bf16 v[204:207], v[178:181], v[106:109], v[204:207]
	v_mfma_f32_16x16x32_bf16 v[220:223], v[178:181], v[122:125], v[220:223]
	ds_read_b64_tr_b16 v[178:179], v243 offset:0
	ds_read_b64_tr_b16 v[180:181], v243 offset:4096
	v_cvt_pk_bf16_f32 v67, v68, v69
	v_cvt_pk_bf16_f32 v68, v70, v71
	v_cvt_pk_bf16_f32 v69, v72, v73
	s_waitcnt lgkmcnt(10)
	v_mfma_f32_16x16x32_bf16 v[192:195], v[224:227], v[110:113], v[192:195]
	v_mfma_f32_16x16x32_bf16 v[208:211], v[224:227], v[126:129], v[208:211]
	ds_read_b64_tr_b16 v[224:225], v244 offset:0
	ds_read_b64_tr_b16 v[226:227], v244 offset:4096
	v_cvt_pk_bf16_f32 v74, v74, v75
	v_cvt_pk_bf16_f32 v75, v76, v77
	v_cvt_pk_bf16_f32 v76, v78, v79
	v_mfma_f32_16x16x32_bf16 v[196:199], v[228:231], v[110:113], v[196:199]
	v_mfma_f32_16x16x32_bf16 v[212:215], v[228:231], v[126:129], v[212:215]
	v_cvt_pk_bf16_f32 v77, v80, v81
	v_cvt_pk_bf16_f32 v82, v82, v83
	v_cvt_pk_bf16_f32 v83, v84, v85
	s_waitcnt lgkmcnt(10)
	v_mfma_f32_16x16x32_bf16 v[200:203], v[232:235], v[110:113], v[200:203]
	v_mfma_f32_16x16x32_bf16 v[216:219], v[232:235], v[126:129], v[216:219]
	v_cvt_pk_bf16_f32 v84, v86, v87
	v_cvt_pk_bf16_f32 v85, v88, v89
	v_cvt_pk_bf16_f32 v90, v90, v91
	v_mfma_f32_16x16x32_bf16 v[204:207], v[236:239], v[110:113], v[204:207]
	v_mfma_f32_16x16x32_bf16 v[220:223], v[236:239], v[126:129], v[220:223]
	v_cvt_pk_bf16_f32 v91, v92, v93
	v_cvt_pk_bf16_f32 v92, v94, v95
	v_cvt_pk_bf16_f32 v93, v96, v97
	s_waitcnt lgkmcnt(6)
	v_mfma_f32_16x16x32_bf16 v[2:5], v[66:69], v[166:169], v[2:5]
	v_mfma_f32_16x16x32_bf16 v[34:37], v[82:85], v[166:169], v[34:37]
	ds_read_b64_tr_b16 v[228:229], v245 offset:0
	ds_read_b64_tr_b16 v[230:231], v245 offset:4096
	v_mfma_f32_16x16x32_bf16 v[6:9], v[66:69], v[170:173], v[6:9]
	v_mfma_f32_16x16x32_bf16 v[38:41], v[82:85], v[170:173], v[38:41]
	ds_read_b64_tr_b16 v[232:233], v246 offset:0
	ds_read_b64_tr_b16 v[234:235], v246 offset:4096
	s_waitcnt lgkmcnt(6)
	v_mfma_f32_16x16x32_bf16 v[10:13], v[66:69], v[174:177], v[10:13]
	v_mfma_f32_16x16x32_bf16 v[42:45], v[82:85], v[174:177], v[42:45]
	ds_read_b64_tr_b16 v[236:237], v247 offset:0
	ds_read_b64_tr_b16 v[238:239], v247 offset:4096
	v_exp_f32_e32 v192, v192
	v_exp_f32_e32 v193, v193
	v_exp_f32_e32 v194, v194
	v_mfma_f32_16x16x32_bf16 v[14:17], v[66:69], v[178:181], v[14:17]
	v_mfma_f32_16x16x32_bf16 v[46:49], v[82:85], v[178:181], v[46:49]
	ds_read_b64_tr_b16 v[166:167], v240 offset:8192
	ds_read_b64_tr_b16 v[168:169], v240 offset:12288
	v_exp_f32_e32 v195, v195
	v_exp_f32_e32 v208, v208
	s_waitcnt lgkmcnt(6)
	v_mfma_f32_16x16x32_bf16 v[18:21], v[66:69], v[224:227], v[18:21]
	v_mfma_f32_16x16x32_bf16 v[50:53], v[82:85], v[224:227], v[50:53]
	ds_read_b64_tr_b16 v[170:171], v241 offset:8192
	ds_read_b64_tr_b16 v[172:173], v241 offset:12288
	v_exp_f32_e32 v209, v209
	v_exp_f32_e32 v210, v210
	v_mfma_f32_16x16x32_bf16 v[22:25], v[66:69], v[228:231], v[22:25]
	v_mfma_f32_16x16x32_bf16 v[54:57], v[82:85], v[228:231], v[54:57]
	ds_read_b64_tr_b16 v[174:175], v242 offset:8192
	ds_read_b64_tr_b16 v[176:177], v242 offset:12288
	v_exp_f32_e32 v211, v211
	v_exp_f32_e32 v196, v196
	v_exp_f32_e32 v197, v197
	s_waitcnt lgkmcnt(6)
	v_mfma_f32_16x16x32_bf16 v[26:29], v[66:69], v[232:235], v[26:29]
	v_mfma_f32_16x16x32_bf16 v[58:61], v[82:85], v[232:235], v[58:61]
	ds_read_b64_tr_b16 v[178:179], v243 offset:8192
	ds_read_b64_tr_b16 v[180:181], v243 offset:12288
	v_exp_f32_e32 v198, v198
	v_exp_f32_e32 v199, v199
	v_mfma_f32_16x16x32_bf16 v[30:33], v[66:69], v[236:239], v[30:33]
	v_mfma_f32_16x16x32_bf16 v[62:65], v[82:85], v[236:239], v[62:65]
	ds_read_b64_tr_b16 v[224:225], v244 offset:8192
	ds_read_b64_tr_b16 v[226:227], v244 offset:12288
	v_exp_f32_e32 v212, v212
	v_exp_f32_e32 v213, v213
	s_waitcnt lgkmcnt(6)
	v_mfma_f32_16x16x32_bf16 v[2:5], v[74:77], v[166:169], v[2:5]
	v_mfma_f32_16x16x32_bf16 v[34:37], v[90:93], v[166:169], v[34:37]
	ds_read_b64_tr_b16 v[228:229], v245 offset:8192
	ds_read_b64_tr_b16 v[230:231], v245 offset:12288
	ds_read_b128 v[166:169], v187 offset:16384
	v_exp_f32_e32 v214, v214
	v_exp_f32_e32 v215, v215
	v_mfma_f32_16x16x32_bf16 v[6:9], v[74:77], v[170:173], v[6:9]
	v_mfma_f32_16x16x32_bf16 v[38:41], v[90:93], v[170:173], v[38:41]
	ds_read_b64_tr_b16 v[232:233], v246 offset:8192
	ds_read_b64_tr_b16 v[234:235], v246 offset:12288
	ds_read_b128 v[170:173], v187 offset:20480
	v_exp_f32_e32 v200, v200
	v_exp_f32_e32 v201, v201
	v_exp_f32_e32 v202, v202
	s_waitcnt lgkmcnt(8)
	v_mfma_f32_16x16x32_bf16 v[10:13], v[74:77], v[174:177], v[10:13]
	v_mfma_f32_16x16x32_bf16 v[42:45], v[90:93], v[174:177], v[42:45]
	ds_read_b64_tr_b16 v[236:237], v247 offset:8192
	ds_read_b64_tr_b16 v[238:239], v247 offset:12288
	ds_read_b128 v[174:177], v187 offset:24576
	v_exp_f32_e32 v203, v203
	v_exp_f32_e32 v216, v216
	v_mfma_f32_16x16x32_bf16 v[14:17], v[74:77], v[178:181], v[14:17]
	v_mfma_f32_16x16x32_bf16 v[46:49], v[90:93], v[178:181], v[46:49]
	ds_read_b128 v[178:181], v187 offset:28672
	v_exp_f32_e32 v217, v217
	v_exp_f32_e32 v218, v218
	s_waitcnt lgkmcnt(8)
	v_mfma_f32_16x16x32_bf16 v[18:21], v[74:77], v[224:227], v[18:21]
	v_mfma_f32_16x16x32_bf16 v[50:53], v[90:93], v[224:227], v[50:53]
	ds_read_b128 v[224:227], v188 offset:16384
	v_exp_f32_e32 v219, v219
	v_exp_f32_e32 v204, v204
	v_exp_f32_e32 v205, v205
	v_mfma_f32_16x16x32_bf16 v[22:25], v[74:77], v[228:231], v[22:25]
	v_mfma_f32_16x16x32_bf16 v[54:57], v[90:93], v[228:231], v[54:57]
	ds_read_b128 v[228:231], v188 offset:20480
	v_exp_f32_e32 v206, v206
	v_exp_f32_e32 v207, v207
	s_waitcnt lgkmcnt(4)
	v_mfma_f32_16x16x32_bf16 v[26:29], v[74:77], v[232:235], v[26:29]
	v_mfma_f32_16x16x32_bf16 v[58:61], v[90:93], v[232:235], v[58:61]
	ds_read_b128 v[232:235], v188 offset:24576
	v_exp_f32_e32 v220, v220
	v_exp_f32_e32 v221, v221
	v_mfma_f32_16x16x32_bf16 v[30:33], v[74:77], v[236:239], v[30:33]
	v_mfma_f32_16x16x32_bf16 v[62:65], v[90:93], v[236:239], v[62:65]
	ds_read_b128 v[236:239], v188 offset:28672
	v_exp_f32_e32 v222, v222
	v_exp_f32_e32 v223, v223
	s_waitcnt vmcnt(0)
	s_barrier
	s_add_i32 s66, s3, s33
	s_cmpk_lt_i32 s66, 0x400
	s_cselect_b32 s66, s66, s3
	s_lshr_b32 s0, s66, 7
	s_lshl_b32 s0, s0, 23
	s_and_b32 s1, s66, 15
	s_lshl_b32 s1, s1, 19
	s_or_b32 s0, s0, s1
	s_bfe_u32 s1, s66, 0x30004
	s_lshl_b32 s1, s1, 8
	s_or_b32 s0, s0, s1
	s_add_u32 s60, s25, s0
	s_addc_u32 s61, s28, 0
	s_add_u32 s18, s21, s0
	s_addc_u32 s19, s24, 0
	s_lshr_b32 s1, s66, 6
	s_mul_i32 s1, s1, 0x110000
	s_add_u32 s62, s9, s1
	s_addc_u32 s63, s20, 0
	s_add_u32 s64, s29, s1
	s_addc_u32 s65, s30, 0
	v_mfma_f32_16x16x32_bf16 v[66:69], v[166:169], v[98:101], 0
	v_mfma_f32_16x16x32_bf16 v[82:85], v[166:169], v[114:117], 0
	ds_read_b128 v[166:169], v189 offset:16384
	v_add_f32_e32 v130, v192, v193
	v_add_f32_e32 v131, v194, v195
	v_add_f32_e32 v130, v196, v130
	v_mfma_f32_16x16x32_bf16 v[70:73], v[170:173], v[98:101], 0
	v_mfma_f32_16x16x32_bf16 v[86:89], v[170:173], v[114:117], 0
	ds_read_b128 v[170:173], v189 offset:20480
	v_add_f32_e32 v131, v197, v131
	v_add_f32_e32 v130, v198, v130
	v_add_f32_e32 v131, v199, v131
	s_waitcnt lgkmcnt(6)
	v_mfma_f32_16x16x32_bf16 v[74:77], v[174:177], v[98:101], 0
	v_mfma_f32_16x16x32_bf16 v[90:93], v[174:177], v[114:117], 0
	ds_read_b128 v[174:177], v189 offset:24576
	v_add_f32_e32 v130, v200, v130
	v_add_f32_e32 v131, v201, v131
	v_add_f32_e32 v130, v202, v130
	v_mfma_f32_16x16x32_bf16 v[78:81], v[178:181], v[98:101], 0
	v_mfma_f32_16x16x32_bf16 v[94:97], v[178:181], v[114:117], 0
	ds_read_b128 v[178:181], v189 offset:28672
	v_add_f32_e32 v131, v203, v131
	v_add_f32_e32 v130, v204, v130
	v_add_f32_e32 v131, v205, v131
	s_waitcnt lgkmcnt(6)
	v_mfma_f32_16x16x32_bf16 v[66:69], v[224:227], v[102:105], v[66:69]
	v_mfma_f32_16x16x32_bf16 v[82:85], v[224:227], v[118:121], v[82:85]
	ds_read_b128 v[224:227], v190 offset:16384
	v_add_f32_e32 v130, v206, v130
	v_add_f32_e32 v131, v207, v131
	v_add_f32_e32 v130, v130, v131
	v_mfma_f32_16x16x32_bf16 v[70:73], v[228:231], v[102:105], v[70:73]
	v_mfma_f32_16x16x32_bf16 v[86:89], v[228:231], v[118:121], v[86:89]
	ds_read_b128 v[228:231], v190 offset:20480
	v_add_f32_e32 v165, v165, v130
	v_add_f32_e32 v132, v208, v209
	v_add_f32_e32 v133, v210, v211
	s_waitcnt lgkmcnt(6)
	v_mfma_f32_16x16x32_bf16 v[74:77], v[232:235], v[102:105], v[74:77]
	v_mfma_f32_16x16x32_bf16 v[90:93], v[232:235], v[118:121], v[90:93]
	ds_read_b128 v[232:235], v190 offset:24576
	v_add_f32_e32 v132, v212, v132
	v_add_f32_e32 v133, v213, v133
	v_add_f32_e32 v132, v214, v132
	v_mfma_f32_16x16x32_bf16 v[78:81], v[236:239], v[102:105], v[78:81]
	v_mfma_f32_16x16x32_bf16 v[94:97], v[236:239], v[118:121], v[94:97]
	ds_read_b128 v[236:239], v190 offset:28672
	v_add_f32_e32 v133, v215, v133
	v_add_f32_e32 v132, v216, v132
	v_add_f32_e32 v133, v217, v133
	s_waitcnt lgkmcnt(6)
	v_mfma_f32_16x16x32_bf16 v[66:69], v[166:169], v[106:109], v[66:69]
	v_mfma_f32_16x16x32_bf16 v[82:85], v[166:169], v[122:125], v[82:85]
	ds_read_b64_tr_b16 v[166:167], v240 offset:32768
	ds_read_b64_tr_b16 v[168:169], v240 offset:36864
	v_add_f32_e32 v132, v218, v132
	v_add_f32_e32 v133, v219, v133
	v_add_f32_e32 v132, v220, v132
	v_mfma_f32_16x16x32_bf16 v[70:73], v[170:173], v[106:109], v[70:73]
	v_mfma_f32_16x16x32_bf16 v[86:89], v[170:173], v[122:125], v[86:89]
	ds_read_b64_tr_b16 v[170:171], v241 offset:32768
	ds_read_b64_tr_b16 v[172:173], v241 offset:36864
	v_add_f32_e32 v133, v221, v133
	v_add_f32_e32 v132, v222, v132
	v_add_f32_e32 v133, v223, v133
	s_waitcnt lgkmcnt(8)
	v_mfma_f32_16x16x32_bf16 v[74:77], v[174:177], v[106:109], v[74:77]
	v_mfma_f32_16x16x32_bf16 v[90:93], v[174:177], v[122:125], v[90:93]
	ds_read_b64_tr_b16 v[174:175], v242 offset:32768
	ds_read_b64_tr_b16 v[176:177], v242 offset:36864
	v_add_f32_e32 v132, v132, v133
	v_add_f32_e32 v163, v163, v132
	v_cvt_pk_bf16_f32 v192, v192, v193
	v_mfma_f32_16x16x32_bf16 v[78:81], v[178:181], v[106:109], v[78:81]
	v_mfma_f32_16x16x32_bf16 v[94:97], v[178:181], v[122:125], v[94:97]
	ds_read_b64_tr_b16 v[178:179], v243 offset:32768
	ds_read_b64_tr_b16 v[180:181], v243 offset:36864
	v_cvt_pk_bf16_f32 v193, v194, v195
	v_cvt_pk_bf16_f32 v194, v196, v197
	v_cvt_pk_bf16_f32 v195, v198, v199
	s_waitcnt lgkmcnt(10)
	v_mfma_f32_16x16x32_bf16 v[66:69], v[224:227], v[110:113], v[66:69]
	v_mfma_f32_16x16x32_bf16 v[82:85], v[224:227], v[126:129], v[82:85]
	ds_read_b64_tr_b16 v[224:225], v244 offset:32768
	ds_read_b64_tr_b16 v[226:227], v244 offset:36864
	v_cvt_pk_bf16_f32 v200, v200, v201
	v_cvt_pk_bf16_f32 v201, v202, v203
	v_cvt_pk_bf16_f32 v202, v204, v205
	v_mfma_f32_16x16x32_bf16 v[70:73], v[228:231], v[110:113], v[70:73]
	v_mfma_f32_16x16x32_bf16 v[86:89], v[228:231], v[126:129], v[86:89]
	v_cvt_pk_bf16_f32 v203, v206, v207
	v_cvt_pk_bf16_f32 v208, v208, v209
	v_cvt_pk_bf16_f32 v209, v210, v211
	s_waitcnt lgkmcnt(10)
	v_mfma_f32_16x16x32_bf16 v[74:77], v[232:235], v[110:113], v[74:77]
	v_mfma_f32_16x16x32_bf16 v[90:93], v[232:235], v[126:129], v[90:93]
	v_cvt_pk_bf16_f32 v210, v212, v213
	v_cvt_pk_bf16_f32 v211, v214, v215
	v_cvt_pk_bf16_f32 v216, v216, v217
	v_mfma_f32_16x16x32_bf16 v[78:81], v[236:239], v[110:113], v[78:81]
	v_mfma_f32_16x16x32_bf16 v[94:97], v[236:239], v[126:129], v[94:97]
	v_cvt_pk_bf16_f32 v217, v218, v219
	v_cvt_pk_bf16_f32 v218, v220, v221
	v_cvt_pk_bf16_f32 v219, v222, v223
	s_waitcnt lgkmcnt(6)
	v_mfma_f32_16x16x32_bf16 v[2:5], v[192:195], v[166:169], v[2:5]
	v_mfma_f32_16x16x32_bf16 v[34:37], v[208:211], v[166:169], v[34:37]
	ds_read_b64_tr_b16 v[228:229], v245 offset:32768
	ds_read_b64_tr_b16 v[230:231], v245 offset:36864
	v_mfma_f32_16x16x32_bf16 v[6:9], v[192:195], v[170:173], v[6:9]
	v_mfma_f32_16x16x32_bf16 v[38:41], v[208:211], v[170:173], v[38:41]
	ds_read_b64_tr_b16 v[232:233], v246 offset:32768
	ds_read_b64_tr_b16 v[234:235], v246 offset:36864
	s_waitcnt lgkmcnt(6)
	v_mfma_f32_16x16x32_bf16 v[10:13], v[192:195], v[174:177], v[10:13]
	v_mfma_f32_16x16x32_bf16 v[42:45], v[208:211], v[174:177], v[42:45]
	ds_read_b64_tr_b16 v[236:237], v247 offset:32768
	ds_read_b64_tr_b16 v[238:239], v247 offset:36864
	v_exp_f32_e32 v66, v66
	v_exp_f32_e32 v67, v67
	v_exp_f32_e32 v68, v68
	v_mfma_f32_16x16x32_bf16 v[14:17], v[192:195], v[178:181], v[14:17]
	v_mfma_f32_16x16x32_bf16 v[46:49], v[208:211], v[178:181], v[46:49]
	ds_read_b64_tr_b16 v[166:167], v240 offset:40960
	ds_read_b64_tr_b16 v[168:169], v240 offset:45056
	v_exp_f32_e32 v69, v69
	v_exp_f32_e32 v82, v82
	s_waitcnt lgkmcnt(6)
	v_mfma_f32_16x16x32_bf16 v[18:21], v[192:195], v[224:227], v[18:21]
	v_mfma_f32_16x16x32_bf16 v[50:53], v[208:211], v[224:227], v[50:53]
	ds_read_b64_tr_b16 v[170:171], v241 offset:40960
	ds_read_b64_tr_b16 v[172:173], v241 offset:45056
	v_exp_f32_e32 v83, v83
	v_exp_f32_e32 v84, v84
	v_mfma_f32_16x16x32_bf16 v[22:25], v[192:195], v[228:231], v[22:25]
	v_mfma_f32_16x16x32_bf16 v[54:57], v[208:211], v[228:231], v[54:57]
	ds_read_b64_tr_b16 v[174:175], v242 offset:40960
	ds_read_b64_tr_b16 v[176:177], v242 offset:45056
	v_exp_f32_e32 v85, v85
	v_exp_f32_e32 v70, v70
	v_exp_f32_e32 v71, v71
	s_waitcnt lgkmcnt(6)
	v_mfma_f32_16x16x32_bf16 v[26:29], v[192:195], v[232:235], v[26:29]
	v_mfma_f32_16x16x32_bf16 v[58:61], v[208:211], v[232:235], v[58:61]
	ds_read_b64_tr_b16 v[178:179], v243 offset:40960
	ds_read_b64_tr_b16 v[180:181], v243 offset:45056
	v_exp_f32_e32 v72, v72
	v_exp_f32_e32 v73, v73
	v_mfma_f32_16x16x32_bf16 v[30:33], v[192:195], v[236:239], v[30:33]
	v_mfma_f32_16x16x32_bf16 v[62:65], v[208:211], v[236:239], v[62:65]
	ds_read_b64_tr_b16 v[224:225], v244 offset:40960
	ds_read_b64_tr_b16 v[226:227], v244 offset:45056
	v_exp_f32_e32 v86, v86
	v_exp_f32_e32 v87, v87
	s_waitcnt lgkmcnt(6)
	v_mfma_f32_16x16x32_bf16 v[2:5], v[200:203], v[166:169], v[2:5]
	v_mfma_f32_16x16x32_bf16 v[34:37], v[216:219], v[166:169], v[34:37]
	ds_read_b64_tr_b16 v[228:229], v245 offset:40960
	ds_read_b64_tr_b16 v[230:231], v245 offset:45056
	ds_read_b128 v[166:169], v187 offset:49152
	v_exp_f32_e32 v88, v88
	v_exp_f32_e32 v89, v89
	v_mfma_f32_16x16x32_bf16 v[6:9], v[200:203], v[170:173], v[6:9]
	v_mfma_f32_16x16x32_bf16 v[38:41], v[216:219], v[170:173], v[38:41]
	ds_read_b64_tr_b16 v[232:233], v246 offset:40960
	ds_read_b64_tr_b16 v[234:235], v246 offset:45056
	ds_read_b128 v[170:173], v187 offset:53248
	v_exp_f32_e32 v74, v74
	v_exp_f32_e32 v75, v75
	v_exp_f32_e32 v76, v76
	s_waitcnt lgkmcnt(8)
	v_mfma_f32_16x16x32_bf16 v[10:13], v[200:203], v[174:177], v[10:13]
	v_mfma_f32_16x16x32_bf16 v[42:45], v[216:219], v[174:177], v[42:45]
	ds_read_b64_tr_b16 v[236:237], v247 offset:40960
	ds_read_b64_tr_b16 v[238:239], v247 offset:45056
	ds_read_b128 v[174:177], v187 offset:57344
	v_exp_f32_e32 v77, v77
	v_exp_f32_e32 v90, v90
	v_mfma_f32_16x16x32_bf16 v[14:17], v[200:203], v[178:181], v[14:17]
	v_mfma_f32_16x16x32_bf16 v[46:49], v[216:219], v[178:181], v[46:49]
	ds_read_b128 v[178:181], v187 offset:61440
	v_exp_f32_e32 v91, v91
	v_exp_f32_e32 v92, v92
	s_waitcnt lgkmcnt(8)
	v_mfma_f32_16x16x32_bf16 v[18:21], v[200:203], v[224:227], v[18:21]
	v_mfma_f32_16x16x32_bf16 v[50:53], v[216:219], v[224:227], v[50:53]
	ds_read_b128 v[224:227], v188 offset:49152
	v_exp_f32_e32 v93, v93
	v_exp_f32_e32 v78, v78
	v_exp_f32_e32 v79, v79
	v_mfma_f32_16x16x32_bf16 v[22:25], v[200:203], v[228:231], v[22:25]
	v_mfma_f32_16x16x32_bf16 v[54:57], v[216:219], v[228:231], v[54:57]
	ds_read_b128 v[228:231], v188 offset:53248
	v_exp_f32_e32 v80, v80
	v_exp_f32_e32 v81, v81
	s_waitcnt lgkmcnt(4)
	v_mfma_f32_16x16x32_bf16 v[26:29], v[200:203], v[232:235], v[26:29]
	v_mfma_f32_16x16x32_bf16 v[58:61], v[216:219], v[232:235], v[58:61]
	ds_read_b128 v[232:235], v188 offset:57344
	v_exp_f32_e32 v94, v94
	v_exp_f32_e32 v95, v95
	v_mfma_f32_16x16x32_bf16 v[30:33], v[200:203], v[236:239], v[30:33]
	v_mfma_f32_16x16x32_bf16 v[62:65], v[216:219], v[236:239], v[62:65]
	ds_read_b128 v[236:239], v188 offset:61440
	v_exp_f32_e32 v96, v96
	v_exp_f32_e32 v97, v97
	s_barrier
	v_mfma_f32_16x16x32_bf16 v[192:195], v[166:169], v[98:101], 0
	v_mfma_f32_16x16x32_bf16 v[208:211], v[166:169], v[114:117], 0
	ds_read_b128 v[166:169], v189 offset:49152
	s_add_i32 m0, s45, 0x0
	v_add_f32_e32 v130, v66, v67
	v_add_f32_e32 v131, v68, v69
	v_add_f32_e32 v130, v70, v130
	global_load_lds_dwordx4 v152, s[64:65]
	v_mfma_f32_16x16x32_bf16 v[196:199], v[170:173], v[98:101], 0
	v_mfma_f32_16x16x32_bf16 v[212:215], v[170:173], v[114:117], 0
	ds_read_b128 v[170:173], v189 offset:53248
	s_add_i32 m0, s45, 0x4000
	v_add_f32_e32 v131, v71, v131
	v_add_f32_e32 v130, v72, v130
	v_add_f32_e32 v131, v73, v131
	global_load_lds_dwordx4 v150, s[62:63]
	s_waitcnt lgkmcnt(6)
	v_mfma_f32_16x16x32_bf16 v[200:203], v[174:177], v[98:101], 0
	v_mfma_f32_16x16x32_bf16 v[216:219], v[174:177], v[114:117], 0
	ds_read_b128 v[174:177], v189 offset:57344
	s_add_i32 m0, s45, 0x2000
	v_add_f32_e32 v130, v74, v130
	v_add_f32_e32 v131, v75, v131
	v_add_f32_e32 v130, v76, v130
	global_load_lds_dwordx4 v153, s[64:65]
	v_mfma_f32_16x16x32_bf16 v[204:207], v[178:181], v[98:101], 0
	v_mfma_f32_16x16x32_bf16 v[220:223], v[178:181], v[114:117], 0
	ds_read_b128 v[178:181], v189 offset:61440
	s_add_i32 m0, s45, 0x6000
	v_add_f32_e32 v131, v77, v131
	v_add_f32_e32 v130, v78, v130
	v_add_f32_e32 v131, v79, v131
	global_load_lds_dwordx4 v151, s[62:63]
	s_add_u32 s62, s62, 0x4000
	s_addc_u32 s63, s63, 0
	s_add_u32 s64, s64, 0x4000
	s_addc_u32 s65, s65, 0
	s_waitcnt lgkmcnt(6)
	v_mfma_f32_16x16x32_bf16 v[192:195], v[224:227], v[102:105], v[192:195]
	v_mfma_f32_16x16x32_bf16 v[208:211], v[224:227], v[118:121], v[208:211]
	ds_read_b128 v[224:227], v190 offset:49152
	v_add_f32_e32 v130, v80, v130
	v_add_f32_e32 v131, v81, v131
	v_add_f32_e32 v130, v130, v131
	v_mfma_f32_16x16x32_bf16 v[196:199], v[228:231], v[102:105], v[196:199]
	v_mfma_f32_16x16x32_bf16 v[212:215], v[228:231], v[118:121], v[212:215]
	ds_read_b128 v[228:231], v190 offset:53248
	v_add_f32_e32 v165, v165, v130
	v_add_f32_e32 v132, v82, v83
	v_add_f32_e32 v133, v84, v85
	s_waitcnt lgkmcnt(6)
	v_mfma_f32_16x16x32_bf16 v[200:203], v[232:235], v[102:105], v[200:203]
	v_mfma_f32_16x16x32_bf16 v[216:219], v[232:235], v[118:121], v[216:219]
	ds_read_b128 v[232:235], v190 offset:57344
	v_add_f32_e32 v132, v86, v132
	v_add_f32_e32 v133, v87, v133
	v_add_f32_e32 v132, v88, v132
	v_mfma_f32_16x16x32_bf16 v[204:207], v[236:239], v[102:105], v[204:207]
	v_mfma_f32_16x16x32_bf16 v[220:223], v[236:239], v[118:121], v[220:223]
	ds_read_b128 v[236:239], v190 offset:61440
	v_add_f32_e32 v133, v89, v133
	v_add_f32_e32 v132, v90, v132
	v_add_f32_e32 v133, v91, v133
	s_waitcnt lgkmcnt(6)
	v_mfma_f32_16x16x32_bf16 v[192:195], v[166:169], v[106:109], v[192:195]
	v_mfma_f32_16x16x32_bf16 v[208:211], v[166:169], v[122:125], v[208:211]
	ds_read_b64_tr_b16 v[166:167], v142 offset:0
	ds_read_b64_tr_b16 v[168:169], v142 offset:4096
	v_add_f32_e32 v132, v92, v132
	v_add_f32_e32 v133, v93, v133
	v_add_f32_e32 v132, v94, v132
	v_mfma_f32_16x16x32_bf16 v[196:199], v[170:173], v[106:109], v[196:199]
	v_mfma_f32_16x16x32_bf16 v[212:215], v[170:173], v[122:125], v[212:215]
	ds_read_b64_tr_b16 v[170:171], v143 offset:0
	ds_read_b64_tr_b16 v[172:173], v143 offset:4096
	v_add_f32_e32 v133, v95, v133
	v_add_f32_e32 v132, v96, v132
	v_add_f32_e32 v133, v97, v133
	s_waitcnt lgkmcnt(8)
	v_mfma_f32_16x16x32_bf16 v[200:203], v[174:177], v[106:109], v[200:203]
	v_mfma_f32_16x16x32_bf16 v[216:219], v[174:177], v[122:125], v[216:219]
	ds_read_b64_tr_b16 v[174:175], v144 offset:0
	ds_read_b64_tr_b16 v[176:177], v144 offset:4096
	v_add_f32_e32 v132, v132, v133
	v_add_f32_e32 v163, v163, v132
	v_cvt_pk_bf16_f32 v66, v66, v67
	v_mfma_f32_16x16x32_bf16 v[204:207], v[178:181], v[106:109], v[204:207]
	v_mfma_f32_16x16x32_bf16 v[220:223], v[178:181], v[122:125], v[220:223]
	ds_read_b64_tr_b16 v[178:179], v145 offset:0
	ds_read_b64_tr_b16 v[180:181], v145 offset:4096
	v_cvt_pk_bf16_f32 v67, v68, v69
	v_cvt_pk_bf16_f32 v68, v70, v71
	v_cvt_pk_bf16_f32 v69, v72, v73
	s_waitcnt lgkmcnt(10)
	v_mfma_f32_16x16x32_bf16 v[192:195], v[224:227], v[110:113], v[192:195]
	v_mfma_f32_16x16x32_bf16 v[208:211], v[224:227], v[126:129], v[208:211]
	ds_read_b64_tr_b16 v[224:225], v146 offset:0
	ds_read_b64_tr_b16 v[226:227], v146 offset:4096
	v_cvt_pk_bf16_f32 v74, v74, v75
	v_cvt_pk_bf16_f32 v75, v76, v77
	v_cvt_pk_bf16_f32 v76, v78, v79
	v_mfma_f32_16x16x32_bf16 v[196:199], v[228:231], v[110:113], v[196:199]
	v_mfma_f32_16x16x32_bf16 v[212:215], v[228:231], v[126:129], v[212:215]
	v_cvt_pk_bf16_f32 v77, v80, v81
	v_cvt_pk_bf16_f32 v82, v82, v83
	v_cvt_pk_bf16_f32 v83, v84, v85
	s_waitcnt lgkmcnt(10)
	v_mfma_f32_16x16x32_bf16 v[200:203], v[232:235], v[110:113], v[200:203]
	v_mfma_f32_16x16x32_bf16 v[216:219], v[232:235], v[126:129], v[216:219]
	v_cvt_pk_bf16_f32 v84, v86, v87
	v_cvt_pk_bf16_f32 v85, v88, v89
	v_cvt_pk_bf16_f32 v90, v90, v91
	v_mfma_f32_16x16x32_bf16 v[204:207], v[236:239], v[110:113], v[204:207]
	v_mfma_f32_16x16x32_bf16 v[220:223], v[236:239], v[126:129], v[220:223]
	v_cvt_pk_bf16_f32 v91, v92, v93
	v_cvt_pk_bf16_f32 v92, v94, v95
	v_cvt_pk_bf16_f32 v93, v96, v97
	s_waitcnt lgkmcnt(6)
	v_mfma_f32_16x16x32_bf16 v[2:5], v[66:69], v[166:169], v[2:5]
	v_mfma_f32_16x16x32_bf16 v[34:37], v[82:85], v[166:169], v[34:37]
	ds_read_b64_tr_b16 v[228:229], v147 offset:0
	ds_read_b64_tr_b16 v[230:231], v147 offset:4096
	v_mfma_f32_16x16x32_bf16 v[6:9], v[66:69], v[170:173], v[6:9]
	v_mfma_f32_16x16x32_bf16 v[38:41], v[82:85], v[170:173], v[38:41]
	ds_read_b64_tr_b16 v[232:233], v148 offset:0
	ds_read_b64_tr_b16 v[234:235], v148 offset:4096
	s_waitcnt lgkmcnt(6)
	v_mfma_f32_16x16x32_bf16 v[10:13], v[66:69], v[174:177], v[10:13]
	v_mfma_f32_16x16x32_bf16 v[42:45], v[82:85], v[174:177], v[42:45]
	ds_read_b64_tr_b16 v[236:237], v149 offset:0
	ds_read_b64_tr_b16 v[238:239], v149 offset:4096
	v_exp_f32_e32 v192, v192
	v_exp_f32_e32 v193, v193
	v_exp_f32_e32 v194, v194
	v_mfma_f32_16x16x32_bf16 v[14:17], v[66:69], v[178:181], v[14:17]
	v_mfma_f32_16x16x32_bf16 v[46:49], v[82:85], v[178:181], v[46:49]
	ds_read_b64_tr_b16 v[166:167], v142 offset:8192
	ds_read_b64_tr_b16 v[168:169], v142 offset:12288
	v_exp_f32_e32 v195, v195
	v_exp_f32_e32 v208, v208
	s_waitcnt lgkmcnt(6)
	v_mfma_f32_16x16x32_bf16 v[18:21], v[66:69], v[224:227], v[18:21]
	v_mfma_f32_16x16x32_bf16 v[50:53], v[82:85], v[224:227], v[50:53]
	ds_read_b64_tr_b16 v[170:171], v143 offset:8192
	ds_read_b64_tr_b16 v[172:173], v143 offset:12288
	v_exp_f32_e32 v209, v209
	v_exp_f32_e32 v210, v210
	v_mfma_f32_16x16x32_bf16 v[22:25], v[66:69], v[228:231], v[22:25]
	v_mfma_f32_16x16x32_bf16 v[54:57], v[82:85], v[228:231], v[54:57]
	ds_read_b64_tr_b16 v[174:175], v144 offset:8192
	ds_read_b64_tr_b16 v[176:177], v144 offset:12288
	v_exp_f32_e32 v211, v211
	v_exp_f32_e32 v196, v196
	v_exp_f32_e32 v197, v197
	s_waitcnt lgkmcnt(6)
	v_mfma_f32_16x16x32_bf16 v[26:29], v[66:69], v[232:235], v[26:29]
	v_mfma_f32_16x16x32_bf16 v[58:61], v[82:85], v[232:235], v[58:61]
	ds_read_b64_tr_b16 v[178:179], v145 offset:8192
	ds_read_b64_tr_b16 v[180:181], v145 offset:12288
	v_exp_f32_e32 v198, v198
	v_exp_f32_e32 v199, v199
	v_mfma_f32_16x16x32_bf16 v[30:33], v[66:69], v[236:239], v[30:33]
	v_mfma_f32_16x16x32_bf16 v[62:65], v[82:85], v[236:239], v[62:65]
	ds_read_b64_tr_b16 v[224:225], v146 offset:8192
	ds_read_b64_tr_b16 v[226:227], v146 offset:12288
	v_exp_f32_e32 v212, v212
	v_exp_f32_e32 v213, v213
	s_waitcnt lgkmcnt(6)
	v_mfma_f32_16x16x32_bf16 v[2:5], v[74:77], v[166:169], v[2:5]
	v_mfma_f32_16x16x32_bf16 v[34:37], v[90:93], v[166:169], v[34:37]
	ds_read_b64_tr_b16 v[228:229], v147 offset:8192
	ds_read_b64_tr_b16 v[230:231], v147 offset:12288
	v_exp_f32_e32 v214, v214
	v_exp_f32_e32 v215, v215
	v_mfma_f32_16x16x32_bf16 v[6:9], v[74:77], v[170:173], v[6:9]
	v_mfma_f32_16x16x32_bf16 v[38:41], v[90:93], v[170:173], v[38:41]
	ds_read_b64_tr_b16 v[232:233], v148 offset:8192
	ds_read_b64_tr_b16 v[234:235], v148 offset:12288
	v_exp_f32_e32 v200, v200
	v_exp_f32_e32 v201, v201
	v_exp_f32_e32 v202, v202
	s_waitcnt lgkmcnt(6)
	v_mfma_f32_16x16x32_bf16 v[10:13], v[74:77], v[174:177], v[10:13]
	v_mfma_f32_16x16x32_bf16 v[42:45], v[90:93], v[174:177], v[42:45]
	ds_read_b64_tr_b16 v[236:237], v149 offset:8192
	ds_read_b64_tr_b16 v[238:239], v149 offset:12288
	v_exp_f32_e32 v203, v203
	v_exp_f32_e32 v216, v216
	v_mfma_f32_16x16x32_bf16 v[14:17], v[74:77], v[178:181], v[14:17]
	v_mfma_f32_16x16x32_bf16 v[46:49], v[90:93], v[178:181], v[46:49]
	v_exp_f32_e32 v217, v217
	v_exp_f32_e32 v218, v218
	s_waitcnt lgkmcnt(4)
	v_mfma_f32_16x16x32_bf16 v[18:21], v[74:77], v[224:227], v[18:21]
	v_mfma_f32_16x16x32_bf16 v[50:53], v[90:93], v[224:227], v[50:53]
	v_exp_f32_e32 v219, v219
	v_exp_f32_e32 v204, v204
	v_exp_f32_e32 v205, v205
	v_mfma_f32_16x16x32_bf16 v[22:25], v[74:77], v[228:231], v[22:25]
	v_mfma_f32_16x16x32_bf16 v[54:57], v[90:93], v[228:231], v[54:57]
	v_exp_f32_e32 v206, v206
	v_exp_f32_e32 v207, v207
	s_waitcnt lgkmcnt(0)
	v_mfma_f32_16x16x32_bf16 v[26:29], v[74:77], v[232:235], v[26:29]
	v_mfma_f32_16x16x32_bf16 v[58:61], v[90:93], v[232:235], v[58:61]
	v_exp_f32_e32 v220, v220
	v_exp_f32_e32 v221, v221
	v_mfma_f32_16x16x32_bf16 v[30:33], v[74:77], v[236:239], v[30:33]
	v_mfma_f32_16x16x32_bf16 v[62:65], v[90:93], v[236:239], v[62:65]
	v_exp_f32_e32 v222, v222
	v_exp_f32_e32 v223, v223
	s_add_i32 m0, s45, 0x8000
	s_nop 0
	global_load_lds_dwordx4 v152, s[64:65]
	s_add_i32 m0, s45, 0xc000
	s_nop 0
	global_load_lds_dwordx4 v150, s[62:63]
	s_add_i32 m0, s45, 0xa000
	s_nop 0
	global_load_lds_dwordx4 v153, s[64:65]
	s_add_i32 m0, s45, 0xe000
	s_nop 0
	global_load_lds_dwordx4 v151, s[62:63]
	s_add_u32 s62, s62, 0x4000
	s_addc_u32 s63, s63, 0
	s_add_u32 s64, s64, 0x4000
	s_addc_u32 s65, s65, 0
	global_load_dwordx4 v[98:101], v154, s[60:61]
	global_load_dwordx4 v[102:105], v154, s[60:61] offset:64
	global_load_dwordx4 v[106:109], v154, s[60:61] offset:128
	global_load_dwordx4 v[110:113], v154, s[60:61] offset:192
	global_load_dwordx4 v[114:117], v155, s[60:61]
	global_load_dwordx4 v[118:121], v155, s[60:61] offset:64
	global_load_dwordx4 v[122:125], v155, s[60:61] offset:128
	global_load_dwordx4 v[126:129], v155, s[60:61] offset:192
	s_barrier
	ds_read_b64_tr_b16 v[166:167], v142 offset:32768
	ds_read_b64_tr_b16 v[168:169], v142 offset:36864
	ds_read_b64_tr_b16 v[170:171], v143 offset:32768
	ds_read_b64_tr_b16 v[172:173], v143 offset:36864
	ds_read_b64_tr_b16 v[174:175], v144 offset:32768
	ds_read_b64_tr_b16 v[176:177], v144 offset:36864
	ds_read_b64_tr_b16 v[178:179], v145 offset:32768
	ds_read_b64_tr_b16 v[180:181], v145 offset:36864
	ds_read_b64_tr_b16 v[224:225], v146 offset:32768
	ds_read_b64_tr_b16 v[226:227], v146 offset:36864
	v_add_f32_e32 v130, v192, v193
	v_add_f32_e32 v131, v194, v195
	v_add_f32_e32 v130, v196, v130
	v_add_f32_e32 v131, v197, v131
	v_add_f32_e32 v130, v198, v130
	v_add_f32_e32 v131, v199, v131
	v_add_f32_e32 v130, v200, v130
	v_add_f32_e32 v131, v201, v131
	v_add_f32_e32 v130, v202, v130
	v_add_f32_e32 v131, v203, v131
	v_add_f32_e32 v130, v204, v130
	v_add_f32_e32 v131, v205, v131
	v_add_f32_e32 v130, v206, v130
	v_add_f32_e32 v131, v207, v131
	v_add_f32_e32 v130, v130, v131
	v_add_f32_e32 v165, v165, v130
	v_add_f32_e32 v132, v208, v209
	v_add_f32_e32 v133, v210, v211
	v_add_f32_e32 v132, v212, v132
	v_add_f32_e32 v133, v213, v133
	v_add_f32_e32 v132, v214, v132
	v_add_f32_e32 v133, v215, v133
	v_add_f32_e32 v132, v216, v132
	v_add_f32_e32 v133, v217, v133
	v_add_f32_e32 v132, v218, v132
	v_add_f32_e32 v133, v219, v133
	v_add_f32_e32 v132, v220, v132
	v_add_f32_e32 v133, v221, v133
	v_add_f32_e32 v132, v222, v132
	v_add_f32_e32 v133, v223, v133
	v_add_f32_e32 v132, v132, v133
	v_add_f32_e32 v163, v163, v132
	v_cvt_pk_bf16_f32 v192, v192, v193
	v_cvt_pk_bf16_f32 v193, v194, v195
	v_cvt_pk_bf16_f32 v194, v196, v197
	v_cvt_pk_bf16_f32 v195, v198, v199
	v_cvt_pk_bf16_f32 v200, v200, v201
	v_cvt_pk_bf16_f32 v201, v202, v203
	v_cvt_pk_bf16_f32 v202, v204, v205
	v_cvt_pk_bf16_f32 v203, v206, v207
	v_cvt_pk_bf16_f32 v208, v208, v209
	v_cvt_pk_bf16_f32 v209, v210, v211
	v_cvt_pk_bf16_f32 v210, v212, v213
	v_cvt_pk_bf16_f32 v211, v214, v215
	v_cvt_pk_bf16_f32 v216, v216, v217
	v_cvt_pk_bf16_f32 v217, v218, v219
	v_cvt_pk_bf16_f32 v218, v220, v221
	v_cvt_pk_bf16_f32 v219, v222, v223
	s_waitcnt lgkmcnt(6)
	v_mfma_f32_16x16x32_bf16 v[2:5], v[192:195], v[166:169], v[2:5]
	v_mfma_f32_16x16x32_bf16 v[34:37], v[208:211], v[166:169], v[34:37]
	ds_read_b64_tr_b16 v[228:229], v147 offset:32768
	ds_read_b64_tr_b16 v[230:231], v147 offset:36864
	v_mfma_f32_16x16x32_bf16 v[6:9], v[192:195], v[170:173], v[6:9]
	v_mfma_f32_16x16x32_bf16 v[38:41], v[208:211], v[170:173], v[38:41]
	ds_read_b64_tr_b16 v[232:233], v148 offset:32768
	ds_read_b64_tr_b16 v[234:235], v148 offset:36864
	s_waitcnt lgkmcnt(6)
	v_mfma_f32_16x16x32_bf16 v[10:13], v[192:195], v[174:177], v[10:13]
	v_mfma_f32_16x16x32_bf16 v[42:45], v[208:211], v[174:177], v[42:45]
	ds_read_b64_tr_b16 v[236:237], v149 offset:32768
	ds_read_b64_tr_b16 v[238:239], v149 offset:36864
	v_mfma_f32_16x16x32_bf16 v[14:17], v[192:195], v[178:181], v[14:17]
	v_mfma_f32_16x16x32_bf16 v[46:49], v[208:211], v[178:181], v[46:49]
	ds_read_b64_tr_b16 v[166:167], v142 offset:40960
	ds_read_b64_tr_b16 v[168:169], v142 offset:45056
	s_waitcnt lgkmcnt(6)
	v_mfma_f32_16x16x32_bf16 v[18:21], v[192:195], v[224:227], v[18:21]
	v_mfma_f32_16x16x32_bf16 v[50:53], v[208:211], v[224:227], v[50:53]
	ds_read_b64_tr_b16 v[170:171], v143 offset:40960
	ds_read_b64_tr_b16 v[172:173], v143 offset:45056
	v_mfma_f32_16x16x32_bf16 v[22:25], v[192:195], v[228:231], v[22:25]
	v_mfma_f32_16x16x32_bf16 v[54:57], v[208:211], v[228:231], v[54:57]
	ds_read_b64_tr_b16 v[174:175], v144 offset:40960
	ds_read_b64_tr_b16 v[176:177], v144 offset:45056
	s_waitcnt lgkmcnt(6)
	v_mfma_f32_16x16x32_bf16 v[26:29], v[192:195], v[232:235], v[26:29]
	v_mfma_f32_16x16x32_bf16 v[58:61], v[208:211], v[232:235], v[58:61]
	ds_read_b64_tr_b16 v[178:179], v145 offset:40960
	ds_read_b64_tr_b16 v[180:181], v145 offset:45056
	v_mfma_f32_16x16x32_bf16 v[30:33], v[192:195], v[236:239], v[30:33]
	v_mfma_f32_16x16x32_bf16 v[62:65], v[208:211], v[236:239], v[62:65]
	ds_read_b64_tr_b16 v[224:225], v146 offset:40960
	ds_read_b64_tr_b16 v[226:227], v146 offset:45056
	s_waitcnt lgkmcnt(6)
	v_mfma_f32_16x16x32_bf16 v[2:5], v[200:203], v[166:169], v[2:5]
	v_mfma_f32_16x16x32_bf16 v[34:37], v[216:219], v[166:169], v[34:37]
	ds_read_b64_tr_b16 v[228:229], v147 offset:40960
	ds_read_b64_tr_b16 v[230:231], v147 offset:45056
	v_mfma_f32_16x16x32_bf16 v[6:9], v[200:203], v[170:173], v[6:9]
	v_mfma_f32_16x16x32_bf16 v[38:41], v[216:219], v[170:173], v[38:41]
	ds_read_b64_tr_b16 v[232:233], v148 offset:40960
	ds_read_b64_tr_b16 v[234:235], v148 offset:45056
	s_waitcnt lgkmcnt(6)
	v_mfma_f32_16x16x32_bf16 v[10:13], v[200:203], v[174:177], v[10:13]
	v_mfma_f32_16x16x32_bf16 v[42:45], v[216:219], v[174:177], v[42:45]
	ds_read_b64_tr_b16 v[236:237], v149 offset:40960
	ds_read_b64_tr_b16 v[238:239], v149 offset:45056
	v_mfma_f32_16x16x32_bf16 v[14:17], v[200:203], v[178:181], v[14:17]
	v_mfma_f32_16x16x32_bf16 v[46:49], v[216:219], v[178:181], v[46:49]
	s_waitcnt lgkmcnt(4)
	v_mfma_f32_16x16x32_bf16 v[18:21], v[200:203], v[224:227], v[18:21]
	v_mfma_f32_16x16x32_bf16 v[50:53], v[216:219], v[224:227], v[50:53]
	v_mfma_f32_16x16x32_bf16 v[22:25], v[200:203], v[228:231], v[22:25]
	v_mfma_f32_16x16x32_bf16 v[54:57], v[216:219], v[228:231], v[54:57]
	s_waitcnt lgkmcnt(0)
	v_mfma_f32_16x16x32_bf16 v[26:29], v[200:203], v[232:235], v[26:29]
	v_mfma_f32_16x16x32_bf16 v[58:61], v[216:219], v[232:235], v[58:61]
	v_mfma_f32_16x16x32_bf16 v[30:33], v[200:203], v[236:239], v[30:33]
	v_mfma_f32_16x16x32_bf16 v[62:65], v[216:219], v[236:239], v[62:65]
	s_barrier
	ds_write_b32 v160, v165
	ds_write_b32 v160, v163 offset:256
	s_waitcnt lgkmcnt(0)
	ds_read_b128 v[66:69], v161 offset:0
	ds_read_b128 v[70:73], v161 offset:64
	ds_read_b128 v[74:77], v161 offset:128
	ds_read_b128 v[78:81], v161 offset:192
	ds_read_b128 v[82:85], v161 offset:256
	ds_read_b128 v[86:89], v161 offset:320
	ds_read_b128 v[90:93], v161 offset:384
	ds_read_b128 v[94:97], v161 offset:448
	s_waitcnt lgkmcnt(0)
	v_add_f32_e32 v66, v66, v70
	v_add_f32_e32 v74, v74, v78
	v_add_f32_e32 v66, v66, v74
	v_rcp_f32_e32 v192, v66
	v_add_f32_e32 v67, v67, v71
	v_add_f32_e32 v75, v75, v79
	v_add_f32_e32 v67, v67, v75
	v_rcp_f32_e32 v193, v67
	v_add_f32_e32 v68, v68, v72
	v_add_f32_e32 v76, v76, v80
	v_add_f32_e32 v68, v68, v76
	v_rcp_f32_e32 v194, v68
	v_add_f32_e32 v69, v69, v73
	v_add_f32_e32 v77, v77, v81
	v_add_f32_e32 v69, v69, v77
	v_rcp_f32_e32 v195, v69
	v_add_f32_e32 v82, v82, v86
	v_add_f32_e32 v90, v90, v94
	v_add_f32_e32 v82, v82, v90
	v_rcp_f32_e32 v196, v82
	v_add_f32_e32 v83, v83, v87
	v_add_f32_e32 v91, v91, v95
	v_add_f32_e32 v83, v83, v91
	v_rcp_f32_e32 v197, v83
	v_add_f32_e32 v84, v84, v88
	v_add_f32_e32 v92, v92, v96
	v_add_f32_e32 v84, v84, v92
	v_rcp_f32_e32 v198, v84
	v_add_f32_e32 v85, v85, v89
	v_add_f32_e32 v93, v93, v97
	v_add_f32_e32 v85, v85, v93
	v_rcp_f32_e32 v199, v85
	s_nop 0
	v_mul_f32_e32 v2, v2, v192
	v_mul_f32_e32 v6, v6, v192
	v_cvt_pk_bf16_f32 v200, v2, v6
	ds_write_b16 v156, v200 offset:0
	ds_write_b16_d16_hi v156, v200 offset:32
	v_mul_f32_e32 v10, v10, v192
	v_mul_f32_e32 v14, v14, v192
	v_cvt_pk_bf16_f32 v201, v10, v14
	ds_write_b16 v156, v201 offset:64
	ds_write_b16_d16_hi v156, v201 offset:96
	v_mul_f32_e32 v18, v18, v192
	v_mul_f32_e32 v22, v22, v192
	v_cvt_pk_bf16_f32 v202, v18, v22
	ds_write_b16 v156, v202 offset:128
	ds_write_b16_d16_hi v156, v202 offset:160
	v_mul_f32_e32 v26, v26, v192
	v_mul_f32_e32 v30, v30, v192
	v_cvt_pk_bf16_f32 v203, v26, v30
	ds_write_b16 v156, v203 offset:192
	ds_write_b16_d16_hi v156, v203 offset:224
	v_mul_f32_e32 v3, v3, v193
	v_mul_f32_e32 v7, v7, v193
	v_cvt_pk_bf16_f32 v204, v3, v7
	ds_write_b16 v156, v204 offset:256
	ds_write_b16_d16_hi v156, v204 offset:288
	v_mul_f32_e32 v11, v11, v193
	v_mul_f32_e32 v15, v15, v193
	v_cvt_pk_bf16_f32 v205, v11, v15
	ds_write_b16 v156, v205 offset:320
	ds_write_b16_d16_hi v156, v205 offset:352
	v_mul_f32_e32 v19, v19, v193
	v_mul_f32_e32 v23, v23, v193
	v_cvt_pk_bf16_f32 v206, v19, v23
	ds_write_b16 v156, v206 offset:384
	ds_write_b16_d16_hi v156, v206 offset:416
	v_mul_f32_e32 v27, v27, v193
	v_mul_f32_e32 v31, v31, v193
	v_cvt_pk_bf16_f32 v207, v27, v31
	ds_write_b16 v156, v207 offset:448
	ds_write_b16_d16_hi v156, v207 offset:480
	v_mul_f32_e32 v4, v4, v194
	v_mul_f32_e32 v8, v8, v194
	v_cvt_pk_bf16_f32 v200, v4, v8
	ds_write_b16 v156, v200 offset:512
	ds_write_b16_d16_hi v156, v200 offset:544
	v_mul_f32_e32 v12, v12, v194
	v_mul_f32_e32 v16, v16, v194
	v_cvt_pk_bf16_f32 v201, v12, v16
	ds_write_b16 v156, v201 offset:576
	ds_write_b16_d16_hi v156, v201 offset:608
	v_mul_f32_e32 v20, v20, v194
	v_mul_f32_e32 v24, v24, v194
	v_cvt_pk_bf16_f32 v202, v20, v24
	ds_write_b16 v156, v202 offset:640
	ds_write_b16_d16_hi v156, v202 offset:672
	v_mul_f32_e32 v28, v28, v194
	v_mul_f32_e32 v32, v32, v194
	v_cvt_pk_bf16_f32 v203, v28, v32
	ds_write_b16 v156, v203 offset:704
	ds_write_b16_d16_hi v156, v203 offset:736
	v_mul_f32_e32 v5, v5, v195
	v_mul_f32_e32 v9, v9, v195
	v_cvt_pk_bf16_f32 v204, v5, v9
	ds_write_b16 v156, v204 offset:768
	ds_write_b16_d16_hi v156, v204 offset:800
	v_mul_f32_e32 v13, v13, v195
	v_mul_f32_e32 v17, v17, v195
	v_cvt_pk_bf16_f32 v205, v13, v17
	ds_write_b16 v156, v205 offset:832
	ds_write_b16_d16_hi v156, v205 offset:864
	v_mul_f32_e32 v21, v21, v195
	v_mul_f32_e32 v25, v25, v195
	v_cvt_pk_bf16_f32 v206, v21, v25
	ds_write_b16 v156, v206 offset:896
	ds_write_b16_d16_hi v156, v206 offset:928
	v_mul_f32_e32 v29, v29, v195
	v_mul_f32_e32 v33, v33, v195
	v_cvt_pk_bf16_f32 v207, v29, v33
	ds_write_b16 v156, v207 offset:960
	ds_write_b16_d16_hi v156, v207 offset:992
	v_mul_f32_e32 v34, v34, v196
	v_mul_f32_e32 v38, v38, v196
	v_cvt_pk_bf16_f32 v200, v34, v38
	ds_write_b16 v156, v200 offset:32768
	ds_write_b16_d16_hi v156, v200 offset:32800
	v_mul_f32_e32 v42, v42, v196
	v_mul_f32_e32 v46, v46, v196
	v_cvt_pk_bf16_f32 v201, v42, v46
	ds_write_b16 v156, v201 offset:32832
	ds_write_b16_d16_hi v156, v201 offset:32864
	v_mul_f32_e32 v50, v50, v196
	v_mul_f32_e32 v54, v54, v196
	v_cvt_pk_bf16_f32 v202, v50, v54
	ds_write_b16 v156, v202 offset:32896
	ds_write_b16_d16_hi v156, v202 offset:32928
	v_mul_f32_e32 v58, v58, v196
	v_mul_f32_e32 v62, v62, v196
	v_cvt_pk_bf16_f32 v203, v58, v62
	ds_write_b16 v156, v203 offset:32960
	ds_write_b16_d16_hi v156, v203 offset:32992
	v_mul_f32_e32 v35, v35, v197
	v_mul_f32_e32 v39, v39, v197
	v_cvt_pk_bf16_f32 v204, v35, v39
	ds_write_b16 v156, v204 offset:33024
	ds_write_b16_d16_hi v156, v204 offset:33056
	v_mul_f32_e32 v43, v43, v197
	v_mul_f32_e32 v47, v47, v197
	v_cvt_pk_bf16_f32 v205, v43, v47
	ds_write_b16 v156, v205 offset:33088
	ds_write_b16_d16_hi v156, v205 offset:33120
	v_mul_f32_e32 v51, v51, v197
	v_mul_f32_e32 v55, v55, v197
	v_cvt_pk_bf16_f32 v206, v51, v55
	ds_write_b16 v156, v206 offset:33152
	ds_write_b16_d16_hi v156, v206 offset:33184
	v_mul_f32_e32 v59, v59, v197
	v_mul_f32_e32 v63, v63, v197
	v_cvt_pk_bf16_f32 v207, v59, v63
	ds_write_b16 v156, v207 offset:33216
	ds_write_b16_d16_hi v156, v207 offset:33248
	v_mul_f32_e32 v36, v36, v198
	v_mul_f32_e32 v40, v40, v198
	v_cvt_pk_bf16_f32 v200, v36, v40
	ds_write_b16 v156, v200 offset:33280
	ds_write_b16_d16_hi v156, v200 offset:33312
	v_mul_f32_e32 v44, v44, v198
	v_mul_f32_e32 v48, v48, v198
	v_cvt_pk_bf16_f32 v201, v44, v48
	ds_write_b16 v156, v201 offset:33344
	ds_write_b16_d16_hi v156, v201 offset:33376
	v_mul_f32_e32 v52, v52, v198
	v_mul_f32_e32 v56, v56, v198
	v_cvt_pk_bf16_f32 v202, v52, v56
	ds_write_b16 v156, v202 offset:33408
	ds_write_b16_d16_hi v156, v202 offset:33440
	v_mul_f32_e32 v60, v60, v198
	v_mul_f32_e32 v64, v64, v198
	v_cvt_pk_bf16_f32 v203, v60, v64
	ds_write_b16 v156, v203 offset:33472
	ds_write_b16_d16_hi v156, v203 offset:33504
	v_mul_f32_e32 v37, v37, v199
	v_mul_f32_e32 v41, v41, v199
	v_cvt_pk_bf16_f32 v204, v37, v41
	ds_write_b16 v156, v204 offset:33536
	ds_write_b16_d16_hi v156, v204 offset:33568
	v_mul_f32_e32 v45, v45, v199
	v_mul_f32_e32 v49, v49, v199
	v_cvt_pk_bf16_f32 v205, v45, v49
	ds_write_b16 v156, v205 offset:33600
	ds_write_b16_d16_hi v156, v205 offset:33632
	v_mul_f32_e32 v53, v53, v199
	v_mul_f32_e32 v57, v57, v199
	v_cvt_pk_bf16_f32 v206, v53, v57
	ds_write_b16 v156, v206 offset:33664
	ds_write_b16_d16_hi v156, v206 offset:33696
	v_mul_f32_e32 v61, v61, v199
	v_mul_f32_e32 v65, v65, v199
	v_cvt_pk_bf16_f32 v207, v61, v65
	ds_write_b16 v156, v207 offset:33728
	ds_write_b16_d16_hi v156, v207 offset:33760
	s_waitcnt lgkmcnt(0)
	ds_read_b128 v[66:69], v157 offset:0
	ds_read_b128 v[70:73], v157 offset:8192
	ds_read_b128 v[74:77], v157 offset:16384
	ds_read_b128 v[78:81], v157 offset:24576
	ds_read_b128 v[82:85], v157 offset:32768
	ds_read_b128 v[86:89], v157 offset:40960
	ds_read_b128 v[90:93], v157 offset:49152
	ds_read_b128 v[94:97], v157 offset:57344
	s_mov_b32 s0, s46
	s_mov_b32 s1, s47
	s_waitcnt lgkmcnt(7)
	global_store_dwordx4 v158, v[66:69], s[0:1]
	s_add_u32 s0, s0, 0x2000
	s_addc_u32 s1, s1, 0
	s_waitcnt lgkmcnt(6)
	global_store_dwordx4 v158, v[70:73], s[0:1]
	s_add_u32 s0, s0, 0x2000
	s_addc_u32 s1, s1, 0
	s_waitcnt lgkmcnt(5)
	global_store_dwordx4 v158, v[74:77], s[0:1]
	s_add_u32 s0, s0, 0x2000
	s_addc_u32 s1, s1, 0
	s_waitcnt lgkmcnt(4)
	global_store_dwordx4 v158, v[78:81], s[0:1]
	s_add_u32 s0, s0, 0x2000
	s_addc_u32 s1, s1, 0
	s_waitcnt lgkmcnt(3)
	global_store_dwordx4 v158, v[82:85], s[0:1]
	s_add_u32 s0, s0, 0x2000
	s_addc_u32 s1, s1, 0
	s_waitcnt lgkmcnt(2)
	global_store_dwordx4 v158, v[86:89], s[0:1]
	s_add_u32 s0, s0, 0x2000
	s_addc_u32 s1, s1, 0
	s_waitcnt lgkmcnt(1)
	global_store_dwordx4 v158, v[90:93], s[0:1]
	s_add_u32 s0, s0, 0x2000
	s_addc_u32 s1, s1, 0
	s_waitcnt lgkmcnt(0)
	global_store_dwordx4 v158, v[94:97], s[0:1]
	s_mov_b32 s46, s18
	s_mov_b32 s47, s19
	v_mov_b32_e32 v2, 0
	v_mov_b32_e32 v3, 0
	v_mov_b32_e32 v4, 0
	v_mov_b32_e32 v5, 0
	v_mov_b32_e32 v6, 0
	v_mov_b32_e32 v7, 0
	v_mov_b32_e32 v8, 0
	v_mov_b32_e32 v9, 0
	v_mov_b32_e32 v10, 0
	v_mov_b32_e32 v11, 0
	v_mov_b32_e32 v12, 0
	v_mov_b32_e32 v13, 0
	v_mov_b32_e32 v14, 0
	v_mov_b32_e32 v15, 0
	v_mov_b32_e32 v16, 0
	v_mov_b32_e32 v17, 0
	v_mov_b32_e32 v18, 0
	v_mov_b32_e32 v19, 0
	v_mov_b32_e32 v20, 0
	v_mov_b32_e32 v21, 0
	v_mov_b32_e32 v22, 0
	v_mov_b32_e32 v23, 0
	v_mov_b32_e32 v24, 0
	v_mov_b32_e32 v25, 0
	v_mov_b32_e32 v26, 0
	v_mov_b32_e32 v27, 0
	v_mov_b32_e32 v28, 0
	v_mov_b32_e32 v29, 0
	v_mov_b32_e32 v30, 0
	v_mov_b32_e32 v31, 0
	v_mov_b32_e32 v32, 0
	v_mov_b32_e32 v33, 0
	v_mov_b32_e32 v34, 0
	v_mov_b32_e32 v35, 0
	v_mov_b32_e32 v36, 0
	v_mov_b32_e32 v37, 0
	v_mov_b32_e32 v38, 0
	v_mov_b32_e32 v39, 0
	v_mov_b32_e32 v40, 0
	v_mov_b32_e32 v41, 0
	v_mov_b32_e32 v42, 0
	v_mov_b32_e32 v43, 0
	v_mov_b32_e32 v44, 0
	v_mov_b32_e32 v45, 0
	v_mov_b32_e32 v46, 0
	v_mov_b32_e32 v47, 0
	v_mov_b32_e32 v48, 0
	v_mov_b32_e32 v49, 0
	v_mov_b32_e32 v50, 0
	v_mov_b32_e32 v51, 0
	v_mov_b32_e32 v52, 0
	v_mov_b32_e32 v53, 0
	v_mov_b32_e32 v54, 0
	v_mov_b32_e32 v55, 0
	v_mov_b32_e32 v56, 0
	v_mov_b32_e32 v57, 0
	v_mov_b32_e32 v58, 0
	v_mov_b32_e32 v59, 0
	v_mov_b32_e32 v60, 0
	v_mov_b32_e32 v61, 0
	v_mov_b32_e32 v62, 0
	v_mov_b32_e32 v63, 0
	v_mov_b32_e32 v64, 0
	v_mov_b32_e32 v65, 0
	v_mov_b32_e32 v165, 0
	v_mov_b32_e32 v163, 0
	s_waitcnt vmcnt(8)
	s_add_i32 s3, s3, s33
	s_cmpk_lt_i32 s3, 0x400
	s_cbranch_scc1 .Lattn_unit
